# P5 tile-to-block remap (A-stationary per XCD) like P4
# speedup vs baseline: 1.1442x; 1.0024x over previous
; #define GEMM_GLOAD(P, kt_) { GEMM_GL1(P, 0, kt_) GEMM_GL1(P, 1, kt_) GEMM_GL1(P, 2, kt_) GEMM_GL1(P, 3, kt_) }
; #define GEMM_LSTORE(P, buf_) { GEMM_LS1(P, 0, buf_) GEMM_LS1(P, 1, buf_) GEMM_LS1(P, 2, buf_) GEMM_LS1(P, 3, buf_) }
; template <bool DEEP>
; DI void gemm_mainloop_t(const u16* __restrict__ Ag, int lda, const u16* __restrict__ Bg, int ldb, int K, char* ldsraw,
;                         f32x16 (&acc)[2][2], int akstep) {
;     ...
;   if (DEEP) {
;     uint4 ya0, ya1, ya2, ya3, yb0, yb1, yb2, yb3;
;     GEMM_GLOAD(x, 0);
;     GEMM_GLOAD(y, 1);
;     GEMM_LSTORE(x, 0);
;     __syncthreads();
;     for (int kt = 0; kt < nk; kt += 2) {
;       if (kt + 2 < nk) GEMM_GLOAD(x, kt + 2);
;       GEMM_COMPUTE(0);
;       GEMM_LSTORE(y, 1);
;       __syncthreads();
;       if (kt + 3 < nk) GEMM_GLOAD(y, kt + 3);
;       GEMM_COMPUTE(1);
;       if (kt + 2 < nk) GEMM_LSTORE(x, 0);
;       __syncthreads();
;     }
; DI void phase5(const Params& p, int l, const float* xin, float* xout, char* lds) {
;     ...
;   for (int tile = blockIdx.x; tile < 128 * 8; tile += gridDim.x) {
;     const int nt = tile & 7, mt = tile >> 3;
;     f32x16 acc[2][2];
;     zero_acc(acc);
;     gemm_mainloop(p.z + (size_t)mt * 128 * ZS, ZS, WOT(l) + (size_t)nt * 128 * 1024, 1024, 1024, lds, acc);
.LBB0_1116:
	s_and_b32 s6, s4, 7
	s_lshr_b32 s5, s4, 3
	s_and_b32 s5, s5, 63
	s_lshr_b32 s0, s4, 9
	s_lshl_b32 s0, s0, 3
	s_lshr_b32 s7, s5, 3
	s_add_i32 s0, s0, s7
	s_lshl_b32 s0, s0, 3
	s_add_i32 s0, s0, s6
	s_and_b32 s5, s5, 7
	s_ashr_i32 s1, s0, 31
	s_mul_i32 s6, s0, 0x198000
	s_waitcnt vmcnt(31)
	s_mul_hi_i32 s7, s0, 0x198000
	s_add_u32 s6, s14, s6
	s_addc_u32 s7, s15, s7
	s_lshl_b32 s8, s5, 18
	s_add_u32 s8, s2, s8
	s_addc_u32 s9, s3, 0
	v_lshrrev_b32_e32 v148, 3, v209
	v_and_b32_e32 v149, 7, v209
	v_lshlrev_b32_e32 v149, 4, v149
	v_mov_b32_e32 v150, v148
	v_mul_u32_u24_e32 v136, 0x3300, v150
	v_add_u32_e32 v136, v136, v149
	v_mul_u32_u24_e32 v140, 0x800, v150
	v_add_u32_e32 v140, v140, v149
	v_add_u32_e32 v150, 32, v148
	v_mul_u32_u24_e32 v137, 0x3300, v150
	v_add_u32_e32 v137, v137, v149
	v_mul_u32_u24_e32 v141, 0x800, v150
	v_add_u32_e32 v141, v141, v149
	v_add_u32_e32 v150, 64, v148
	v_mul_u32_u24_e32 v138, 0x3300, v150
	v_add_u32_e32 v138, v138, v149
	v_mul_u32_u24_e32 v142, 0x800, v150
	v_add_u32_e32 v142, v142, v149
	v_add_u32_e32 v150, 96, v148
	v_mul_u32_u24_e32 v139, 0x3300, v150
	v_add_u32_e32 v139, v139, v149
	v_mul_u32_u24_e32 v143, 0x800, v150
	v_add_u32_e32 v143, v143, v149
	v_mul_u32_u24_e32 v144, 0x90, v148
	v_add_u32_e32 v144, v144, v149
	v_add_u32_e32 v145, 0x1200, v144
	v_and_b32_e32 v148, 31, v209
	v_bfe_u32 v149, v209, 5, 1
	v_lshlrev_b32_e32 v149, 4, v149
	v_bfe_u32 v150, v209, 7, 1
	v_lshl_add_u32 v150, v150, 6, v148
	v_mul_u32_u24_e32 v146, 0x90, v150
	v_add_u32_e32 v146, v146, v149
	v_bfe_u32 v150, v209, 6, 1
	v_lshl_add_u32 v150, v150, 6, v148
	v_mul_u32_u24_e32 v147, 0x90, v150
	v_add_u32_e32 v147, v147, v149
	global_load_dwordx4 v[66:69], v136, s[6:7]
	global_load_dwordx4 v[70:73], v140, s[8:9]
	global_load_dwordx4 v[74:77], v137, s[6:7]
	global_load_dwordx4 v[78:81], v141, s[8:9]
	global_load_dwordx4 v[82:85], v138, s[6:7]
	global_load_dwordx4 v[86:89], v142, s[8:9]
	global_load_dwordx4 v[90:93], v139, s[6:7]
	global_load_dwordx4 v[94:97], v143, s[8:9]
	global_load_dwordx4 v[98:101], v136, s[6:7] offset:128
	global_load_dwordx4 v[102:105], v140, s[8:9] offset:128
	global_load_dwordx4 v[106:109], v137, s[6:7] offset:128
	global_load_dwordx4 v[110:113], v141, s[8:9] offset:128
	global_load_dwordx4 v[114:117], v138, s[6:7] offset:128
	global_load_dwordx4 v[118:121], v142, s[8:9] offset:128
	global_load_dwordx4 v[122:125], v139, s[6:7] offset:128
	global_load_dwordx4 v[126:129], v143, s[8:9] offset:128
	s_waitcnt vmcnt(15)
	ds_write_b128 v144, v[66:69]
	s_waitcnt vmcnt(14)
	ds_write_b128 v144, v[70:73] offset:36864
	s_waitcnt vmcnt(13)
	ds_write_b128 v144, v[74:77] offset:4608
	s_waitcnt vmcnt(12)
	ds_write_b128 v144, v[78:81] offset:41472
	s_waitcnt vmcnt(11)
	ds_write_b128 v144, v[82:85] offset:9216
	s_waitcnt vmcnt(10)
	ds_write_b128 v144, v[86:89] offset:46080
	s_waitcnt vmcnt(9)
	ds_write_b128 v144, v[90:93] offset:13824
	s_waitcnt vmcnt(8)
	ds_write_b128 v144, v[94:97] offset:50688
	s_waitcnt lgkmcnt(0)
	s_barrier
	s_setprio 1
	ds_read_b128 v[154:157], v147 offset:36864
	ds_read_b128 v[158:161], v146
	ds_read_b128 v[162:165], v147 offset:41472
	ds_read_b128 v[166:169], v146 offset:4608
	s_waitcnt lgkmcnt(2)
	v_mfma_f32_32x32x16_f16 v[50:65], v[154:157], v[158:161], 0
	global_load_dwordx4 v[66:69], v136, s[6:7] offset:256
	s_waitcnt lgkmcnt(1)
	v_mfma_f32_32x32x16_f16 v[34:49], v[162:165], v[158:161], 0
	ds_read_b128 v[158:161], v146 offset:32
	s_waitcnt vmcnt(8)
	ds_write_b128 v144, v[98:101] offset:18432
	s_waitcnt lgkmcnt(2)
	v_mfma_f32_32x32x16_f16 v[18:33], v[154:157], v[166:169], 0
	ds_read_b128 v[154:157], v147 offset:36896
	global_load_dwordx4 v[70:73], v140, s[8:9] offset:256
	v_mfma_f32_32x32x16_f16 v[2:17], v[162:165], v[166:169], 0
	ds_read_b128 v[162:165], v147 offset:41504
	ds_read_b128 v[166:169], v146 offset:4640
	s_waitcnt vmcnt(8)
	ds_write_b128 v144, v[102:105] offset:55296
	s_waitcnt lgkmcnt(3)
	v_mfma_f32_32x32x16_f16 v[50:65], v[154:157], v[158:161], v[50:65]
	global_load_dwordx4 v[74:77], v137, s[6:7] offset:256
	s_waitcnt lgkmcnt(2)
	v_mfma_f32_32x32x16_f16 v[34:49], v[162:165], v[158:161], v[34:49]
	ds_read_b128 v[158:161], v146 offset:64
	s_waitcnt vmcnt(8)
	ds_write_b128 v144, v[106:109] offset:23040
	s_waitcnt lgkmcnt(3)
	v_mfma_f32_32x32x16_f16 v[18:33], v[154:157], v[166:169], v[18:33]
	ds_read_b128 v[154:157], v147 offset:36928
	global_load_dwordx4 v[78:81], v141, s[8:9] offset:256
	v_mfma_f32_32x32x16_f16 v[2:17], v[162:165], v[166:169], v[2:17]
	ds_read_b128 v[162:165], v147 offset:41536
	ds_read_b128 v[166:169], v146 offset:4672
	s_waitcnt vmcnt(8)
	ds_write_b128 v144, v[110:113] offset:59904
	s_waitcnt lgkmcnt(3)
	v_mfma_f32_32x32x16_f16 v[50:65], v[154:157], v[158:161], v[50:65]
	global_load_dwordx4 v[82:85], v138, s[6:7] offset:256
	s_waitcnt lgkmcnt(2)
	v_mfma_f32_32x32x16_f16 v[34:49], v[162:165], v[158:161], v[34:49]
	ds_read_b128 v[158:161], v146 offset:96
	s_waitcnt vmcnt(8)
	ds_write_b128 v144, v[114:117] offset:27648
	s_waitcnt lgkmcnt(3)
	v_mfma_f32_32x32x16_f16 v[18:33], v[154:157], v[166:169], v[18:33]
	ds_read_b128 v[154:157], v147 offset:36960
	global_load_dwordx4 v[86:89], v142, s[8:9] offset:256
	v_mfma_f32_32x32x16_f16 v[2:17], v[162:165], v[166:169], v[2:17]
	ds_read_b128 v[162:165], v147 offset:41568
	ds_read_b128 v[166:169], v146 offset:4704
	s_waitcnt vmcnt(8)
	ds_write_b128 v144, v[118:121] offset:64512
	s_waitcnt lgkmcnt(3)
	v_mfma_f32_32x32x16_f16 v[50:65], v[154:157], v[158:161], v[50:65]
	global_load_dwordx4 v[90:93], v139, s[6:7] offset:256
	s_waitcnt lgkmcnt(2)
	v_mfma_f32_32x32x16_f16 v[34:49], v[162:165], v[158:161], v[34:49]
	s_waitcnt vmcnt(8)
	ds_write_b128 v144, v[122:125] offset:32256
	s_waitcnt lgkmcnt(2)
	v_mfma_f32_32x32x16_f16 v[18:33], v[154:157], v[166:169], v[18:33]
	global_load_dwordx4 v[94:97], v143, s[8:9] offset:256
	v_mfma_f32_32x32x16_f16 v[2:17], v[162:165], v[166:169], v[2:17]
	s_waitcnt vmcnt(8)
	ds_write_b128 v145, v[126:129] offset:64512
	s_setprio 0
	s_waitcnt lgkmcnt(0)
	s_barrier
; #define GEMM_GLOAD(P, kt_) { GEMM_GL1(P, 0, kt_) GEMM_GL1(P, 1, kt_) GEMM_GL1(P, 2, kt_) GEMM_GL1(P, 3, kt_) }
; #define GEMM_LSTORE(P, buf_) { GEMM_LS1(P, 0, buf_) GEMM_LS1(P, 1, buf_) GEMM_LS1(P, 2, buf_) GEMM_LS1(P, 3, buf_) }
; template <bool DEEP>
; DI void gemm_mainloop_t(const u16* __restrict__ Ag, int lda, const u16* __restrict__ Bg, int ldb, int K, char* ldsraw,
;                         f32x16 (&acc)[2][2], int akstep) {
;     ...
;   if (DEEP) {
;     uint4 ya0, ya1, ya2, ya3, yb0, yb1, yb2, yb3;
;     GEMM_GLOAD(x, 0);
;     GEMM_GLOAD(y, 1);
;     GEMM_LSTORE(x, 0);
;     __syncthreads();
;     for (int kt = 0; kt < nk; kt += 2) {
;       if (kt + 2 < nk) GEMM_GLOAD(x, kt + 2);
;       GEMM_COMPUTE(0);
;       GEMM_LSTORE(y, 1);
;       __syncthreads();
;       if (kt + 3 < nk) GEMM_GLOAD(y, kt + 3);
;       GEMM_COMPUTE(1);
;       if (kt + 2 < nk) GEMM_LSTORE(x, 0);
;       __syncthreads();
;     }
	s_setprio 1
	ds_read_b128 v[154:157], v147 offset:55296
	ds_read_b128 v[158:161], v146 offset:18432
	ds_read_b128 v[162:165], v147 offset:59904
	ds_read_b128 v[166:169], v146 offset:23040
	s_waitcnt lgkmcnt(2)
	v_mfma_f32_32x32x16_f16 v[50:65], v[154:157], v[158:161], v[50:65]
	global_load_dwordx4 v[98:101], v136, s[6:7] offset:384
	s_waitcnt lgkmcnt(1)
	v_mfma_f32_32x32x16_f16 v[34:49], v[162:165], v[158:161], v[34:49]
	ds_read_b128 v[158:161], v146 offset:18464
	s_waitcnt vmcnt(8)
	ds_write_b128 v144, v[66:69]
	s_waitcnt lgkmcnt(2)
	v_mfma_f32_32x32x16_f16 v[18:33], v[154:157], v[166:169], v[18:33]
	ds_read_b128 v[154:157], v147 offset:55328
	global_load_dwordx4 v[102:105], v140, s[8:9] offset:384
	v_mfma_f32_32x32x16_f16 v[2:17], v[162:165], v[166:169], v[2:17]
	ds_read_b128 v[162:165], v147 offset:59936
	ds_read_b128 v[166:169], v146 offset:23072
	s_waitcnt vmcnt(8)
	ds_write_b128 v144, v[70:73] offset:36864
	s_waitcnt lgkmcnt(3)
	v_mfma_f32_32x32x16_f16 v[50:65], v[154:157], v[158:161], v[50:65]
	global_load_dwordx4 v[106:109], v137, s[6:7] offset:384
	s_waitcnt lgkmcnt(2)
	v_mfma_f32_32x32x16_f16 v[34:49], v[162:165], v[158:161], v[34:49]
	ds_read_b128 v[158:161], v146 offset:18496
	s_waitcnt vmcnt(8)
	ds_write_b128 v144, v[74:77] offset:4608
	s_waitcnt lgkmcnt(3)
	v_mfma_f32_32x32x16_f16 v[18:33], v[154:157], v[166:169], v[18:33]
	ds_read_b128 v[154:157], v147 offset:55360
	global_load_dwordx4 v[110:113], v141, s[8:9] offset:384
	v_mfma_f32_32x32x16_f16 v[2:17], v[162:165], v[166:169], v[2:17]
	ds_read_b128 v[162:165], v147 offset:59968
	ds_read_b128 v[166:169], v146 offset:23104
	s_waitcnt vmcnt(8)
	ds_write_b128 v144, v[78:81] offset:41472
	s_waitcnt lgkmcnt(3)
	v_mfma_f32_32x32x16_f16 v[50:65], v[154:157], v[158:161], v[50:65]
	global_load_dwordx4 v[114:117], v138, s[6:7] offset:384
	s_waitcnt lgkmcnt(2)
	v_mfma_f32_32x32x16_f16 v[34:49], v[162:165], v[158:161], v[34:49]
	ds_read_b128 v[158:161], v146 offset:18528
	s_waitcnt vmcnt(8)
	ds_write_b128 v144, v[82:85] offset:9216
	s_waitcnt lgkmcnt(3)
	v_mfma_f32_32x32x16_f16 v[18:33], v[154:157], v[166:169], v[18:33]
	ds_read_b128 v[154:157], v147 offset:55392
	global_load_dwordx4 v[118:121], v142, s[8:9] offset:384
	v_mfma_f32_32x32x16_f16 v[2:17], v[162:165], v[166:169], v[2:17]
	ds_read_b128 v[162:165], v147 offset:60000
	ds_read_b128 v[166:169], v146 offset:23136
	s_waitcnt vmcnt(8)
	ds_write_b128 v144, v[86:89] offset:46080
	s_waitcnt lgkmcnt(3)
	v_mfma_f32_32x32x16_f16 v[50:65], v[154:157], v[158:161], v[50:65]
	global_load_dwordx4 v[122:125], v139, s[6:7] offset:384
	s_waitcnt lgkmcnt(2)
	v_mfma_f32_32x32x16_f16 v[34:49], v[162:165], v[158:161], v[34:49]
	s_waitcnt vmcnt(8)
	ds_write_b128 v144, v[90:93] offset:13824
	s_waitcnt lgkmcnt(2)
	v_mfma_f32_32x32x16_f16 v[18:33], v[154:157], v[166:169], v[18:33]
	global_load_dwordx4 v[126:129], v143, s[8:9] offset:384
	v_mfma_f32_32x32x16_f16 v[2:17], v[162:165], v[166:169], v[2:17]
	s_waitcnt vmcnt(8)
	ds_write_b128 v144, v[94:97] offset:50688
	s_setprio 0
	s_waitcnt lgkmcnt(0)
	s_barrier
	s_setprio 1
	ds_read_b128 v[154:157], v147 offset:36864
	ds_read_b128 v[158:161], v146
	ds_read_b128 v[162:165], v147 offset:41472
	ds_read_b128 v[166:169], v146 offset:4608
	s_waitcnt lgkmcnt(2)
	v_mfma_f32_32x32x16_f16 v[50:65], v[154:157], v[158:161], v[50:65]
	global_load_dwordx4 v[66:69], v136, s[6:7] offset:512
	s_waitcnt lgkmcnt(1)
	v_mfma_f32_32x32x16_f16 v[34:49], v[162:165], v[158:161], v[34:49]
	ds_read_b128 v[158:161], v146 offset:32
	s_waitcnt vmcnt(8)
	ds_write_b128 v144, v[98:101] offset:18432
	s_waitcnt lgkmcnt(2)
	v_mfma_f32_32x32x16_f16 v[18:33], v[154:157], v[166:169], v[18:33]
	ds_read_b128 v[154:157], v147 offset:36896
	global_load_dwordx4 v[70:73], v140, s[8:9] offset:512
	v_mfma_f32_32x32x16_f16 v[2:17], v[162:165], v[166:169], v[2:17]
	ds_read_b128 v[162:165], v147 offset:41504
	ds_read_b128 v[166:169], v146 offset:4640
	s_waitcnt vmcnt(8)
	ds_write_b128 v144, v[102:105] offset:55296
	s_waitcnt lgkmcnt(3)
	v_mfma_f32_32x32x16_f16 v[50:65], v[154:157], v[158:161], v[50:65]
	global_load_dwordx4 v[74:77], v137, s[6:7] offset:512
	s_waitcnt lgkmcnt(2)
	v_mfma_f32_32x32x16_f16 v[34:49], v[162:165], v[158:161], v[34:49]
	ds_read_b128 v[158:161], v146 offset:64
	s_waitcnt vmcnt(8)
	ds_write_b128 v144, v[106:109] offset:23040
	s_waitcnt lgkmcnt(3)
	v_mfma_f32_32x32x16_f16 v[18:33], v[154:157], v[166:169], v[18:33]
	ds_read_b128 v[154:157], v147 offset:36928
	global_load_dwordx4 v[78:81], v141, s[8:9] offset:512
	v_mfma_f32_32x32x16_f16 v[2:17], v[162:165], v[166:169], v[2:17]
	ds_read_b128 v[162:165], v147 offset:41536
	ds_read_b128 v[166:169], v146 offset:4672
	s_waitcnt vmcnt(8)
	ds_write_b128 v144, v[110:113] offset:59904
	s_waitcnt lgkmcnt(3)
	v_mfma_f32_32x32x16_f16 v[50:65], v[154:157], v[158:161], v[50:65]
	global_load_dwordx4 v[82:85], v138, s[6:7] offset:512
	s_waitcnt lgkmcnt(2)
	v_mfma_f32_32x32x16_f16 v[34:49], v[162:165], v[158:161], v[34:49]
	ds_read_b128 v[158:161], v146 offset:96
	s_waitcnt vmcnt(8)
	ds_write_b128 v144, v[114:117] offset:27648
	s_waitcnt lgkmcnt(3)
	v_mfma_f32_32x32x16_f16 v[18:33], v[154:157], v[166:169], v[18:33]
	ds_read_b128 v[154:157], v147 offset:36960
	global_load_dwordx4 v[86:89], v142, s[8:9] offset:512
	v_mfma_f32_32x32x16_f16 v[2:17], v[162:165], v[166:169], v[2:17]
	ds_read_b128 v[162:165], v147 offset:41568
	ds_read_b128 v[166:169], v146 offset:4704
	s_waitcnt vmcnt(8)
	ds_write_b128 v144, v[118:121] offset:64512
	s_waitcnt lgkmcnt(3)
	v_mfma_f32_32x32x16_f16 v[50:65], v[154:157], v[158:161], v[50:65]
	global_load_dwordx4 v[90:93], v139, s[6:7] offset:512
	s_waitcnt lgkmcnt(2)
	v_mfma_f32_32x32x16_f16 v[34:49], v[162:165], v[158:161], v[34:49]
	s_waitcnt vmcnt(8)
	ds_write_b128 v144, v[122:125] offset:32256
	s_waitcnt lgkmcnt(2)
	v_mfma_f32_32x32x16_f16 v[18:33], v[154:157], v[166:169], v[18:33]
	global_load_dwordx4 v[94:97], v143, s[8:9] offset:512
	v_mfma_f32_32x32x16_f16 v[2:17], v[162:165], v[166:169], v[2:17]
	s_waitcnt vmcnt(8)
	ds_write_b128 v145, v[126:129] offset:64512
	s_setprio 0
	s_waitcnt lgkmcnt(0)
	s_barrier
; #define GEMM_GLOAD(P, kt_) { GEMM_GL1(P, 0, kt_) GEMM_GL1(P, 1, kt_) GEMM_GL1(P, 2, kt_) GEMM_GL1(P, 3, kt_) }
; #define GEMM_LSTORE(P, buf_) { GEMM_LS1(P, 0, buf_) GEMM_LS1(P, 1, buf_) GEMM_LS1(P, 2, buf_) GEMM_LS1(P, 3, buf_) }
; template <bool DEEP>
; DI void gemm_mainloop_t(const u16* __restrict__ Ag, int lda, const u16* __restrict__ Bg, int ldb, int K, char* ldsraw,
;                         f32x16 (&acc)[2][2], int akstep) {
;     ...
;   if (DEEP) {
;     uint4 ya0, ya1, ya2, ya3, yb0, yb1, yb2, yb3;
;     GEMM_GLOAD(x, 0);
;     GEMM_GLOAD(y, 1);
;     GEMM_LSTORE(x, 0);
;     __syncthreads();
;     for (int kt = 0; kt < nk; kt += 2) {
;       if (kt + 2 < nk) GEMM_GLOAD(x, kt + 2);
;       GEMM_COMPUTE(0);
;       GEMM_LSTORE(y, 1);
;       __syncthreads();
;       if (kt + 3 < nk) GEMM_GLOAD(y, kt + 3);
;       GEMM_COMPUTE(1);
;       if (kt + 2 < nk) GEMM_LSTORE(x, 0);
;       __syncthreads();
;     }
	s_setprio 1
	ds_read_b128 v[154:157], v147 offset:55296
	ds_read_b128 v[158:161], v146 offset:18432
	ds_read_b128 v[162:165], v147 offset:59904
	ds_read_b128 v[166:169], v146 offset:23040
	s_waitcnt lgkmcnt(2)
	v_mfma_f32_32x32x16_f16 v[50:65], v[154:157], v[158:161], v[50:65]
	global_load_dwordx4 v[98:101], v136, s[6:7] offset:640
	s_waitcnt lgkmcnt(1)
	v_mfma_f32_32x32x16_f16 v[34:49], v[162:165], v[158:161], v[34:49]
	ds_read_b128 v[158:161], v146 offset:18464
	s_waitcnt vmcnt(8)
	ds_write_b128 v144, v[66:69]
	s_waitcnt lgkmcnt(2)
	v_mfma_f32_32x32x16_f16 v[18:33], v[154:157], v[166:169], v[18:33]
	ds_read_b128 v[154:157], v147 offset:55328
	global_load_dwordx4 v[102:105], v140, s[8:9] offset:640
	v_mfma_f32_32x32x16_f16 v[2:17], v[162:165], v[166:169], v[2:17]
	ds_read_b128 v[162:165], v147 offset:59936
	ds_read_b128 v[166:169], v146 offset:23072
	s_waitcnt vmcnt(8)
	ds_write_b128 v144, v[70:73] offset:36864
	s_waitcnt lgkmcnt(3)
	v_mfma_f32_32x32x16_f16 v[50:65], v[154:157], v[158:161], v[50:65]
	global_load_dwordx4 v[106:109], v137, s[6:7] offset:640
	s_waitcnt lgkmcnt(2)
	v_mfma_f32_32x32x16_f16 v[34:49], v[162:165], v[158:161], v[34:49]
	ds_read_b128 v[158:161], v146 offset:18496
	s_waitcnt vmcnt(8)
	ds_write_b128 v144, v[74:77] offset:4608
	s_waitcnt lgkmcnt(3)
	v_mfma_f32_32x32x16_f16 v[18:33], v[154:157], v[166:169], v[18:33]
	ds_read_b128 v[154:157], v147 offset:55360
	global_load_dwordx4 v[110:113], v141, s[8:9] offset:640
	v_mfma_f32_32x32x16_f16 v[2:17], v[162:165], v[166:169], v[2:17]
	ds_read_b128 v[162:165], v147 offset:59968
	ds_read_b128 v[166:169], v146 offset:23104
	s_waitcnt vmcnt(8)
	ds_write_b128 v144, v[78:81] offset:41472
	s_waitcnt lgkmcnt(3)
	v_mfma_f32_32x32x16_f16 v[50:65], v[154:157], v[158:161], v[50:65]
	global_load_dwordx4 v[114:117], v138, s[6:7] offset:640
	s_waitcnt lgkmcnt(2)
	v_mfma_f32_32x32x16_f16 v[34:49], v[162:165], v[158:161], v[34:49]
	ds_read_b128 v[158:161], v146 offset:18528
	s_waitcnt vmcnt(8)
	ds_write_b128 v144, v[82:85] offset:9216
	s_waitcnt lgkmcnt(3)
	v_mfma_f32_32x32x16_f16 v[18:33], v[154:157], v[166:169], v[18:33]
	ds_read_b128 v[154:157], v147 offset:55392
	global_load_dwordx4 v[118:121], v142, s[8:9] offset:640
	v_mfma_f32_32x32x16_f16 v[2:17], v[162:165], v[166:169], v[2:17]
	ds_read_b128 v[162:165], v147 offset:60000
	ds_read_b128 v[166:169], v146 offset:23136
	s_waitcnt vmcnt(8)
	ds_write_b128 v144, v[86:89] offset:46080
	s_waitcnt lgkmcnt(3)
	v_mfma_f32_32x32x16_f16 v[50:65], v[154:157], v[158:161], v[50:65]
	global_load_dwordx4 v[122:125], v139, s[6:7] offset:640
	s_waitcnt lgkmcnt(2)
	v_mfma_f32_32x32x16_f16 v[34:49], v[162:165], v[158:161], v[34:49]
	s_waitcnt vmcnt(8)
	ds_write_b128 v144, v[90:93] offset:13824
	s_waitcnt lgkmcnt(2)
	v_mfma_f32_32x32x16_f16 v[18:33], v[154:157], v[166:169], v[18:33]
	global_load_dwordx4 v[126:129], v143, s[8:9] offset:640
	v_mfma_f32_32x32x16_f16 v[2:17], v[162:165], v[166:169], v[2:17]
	s_waitcnt vmcnt(8)
	ds_write_b128 v144, v[94:97] offset:50688
	s_setprio 0
	s_waitcnt lgkmcnt(0)
	s_barrier
	s_setprio 1
	ds_read_b128 v[154:157], v147 offset:36864
	ds_read_b128 v[158:161], v146
	ds_read_b128 v[162:165], v147 offset:41472
	ds_read_b128 v[166:169], v146 offset:4608
	s_waitcnt lgkmcnt(2)
	v_mfma_f32_32x32x16_f16 v[50:65], v[154:157], v[158:161], v[50:65]
	global_load_dwordx4 v[66:69], v136, s[6:7] offset:768
	s_waitcnt lgkmcnt(1)
	v_mfma_f32_32x32x16_f16 v[34:49], v[162:165], v[158:161], v[34:49]
	ds_read_b128 v[158:161], v146 offset:32
	s_waitcnt vmcnt(8)
	ds_write_b128 v144, v[98:101] offset:18432
	s_waitcnt lgkmcnt(2)
	v_mfma_f32_32x32x16_f16 v[18:33], v[154:157], v[166:169], v[18:33]
	ds_read_b128 v[154:157], v147 offset:36896
	global_load_dwordx4 v[70:73], v140, s[8:9] offset:768
	v_mfma_f32_32x32x16_f16 v[2:17], v[162:165], v[166:169], v[2:17]
	ds_read_b128 v[162:165], v147 offset:41504
	ds_read_b128 v[166:169], v146 offset:4640
	s_waitcnt vmcnt(8)
	ds_write_b128 v144, v[102:105] offset:55296
	s_waitcnt lgkmcnt(3)
	v_mfma_f32_32x32x16_f16 v[50:65], v[154:157], v[158:161], v[50:65]
	global_load_dwordx4 v[74:77], v137, s[6:7] offset:768
	s_waitcnt lgkmcnt(2)
	v_mfma_f32_32x32x16_f16 v[34:49], v[162:165], v[158:161], v[34:49]
	ds_read_b128 v[158:161], v146 offset:64
	s_waitcnt vmcnt(8)
	ds_write_b128 v144, v[106:109] offset:23040
	s_waitcnt lgkmcnt(3)
	v_mfma_f32_32x32x16_f16 v[18:33], v[154:157], v[166:169], v[18:33]
	ds_read_b128 v[154:157], v147 offset:36928
	global_load_dwordx4 v[78:81], v141, s[8:9] offset:768
	v_mfma_f32_32x32x16_f16 v[2:17], v[162:165], v[166:169], v[2:17]
	ds_read_b128 v[162:165], v147 offset:41536
	ds_read_b128 v[166:169], v146 offset:4672
	s_waitcnt vmcnt(8)
	ds_write_b128 v144, v[110:113] offset:59904
	s_waitcnt lgkmcnt(3)
	v_mfma_f32_32x32x16_f16 v[50:65], v[154:157], v[158:161], v[50:65]
	global_load_dwordx4 v[82:85], v138, s[6:7] offset:768
	s_waitcnt lgkmcnt(2)
	v_mfma_f32_32x32x16_f16 v[34:49], v[162:165], v[158:161], v[34:49]
	ds_read_b128 v[158:161], v146 offset:96
	s_waitcnt vmcnt(8)
	ds_write_b128 v144, v[114:117] offset:27648
	s_waitcnt lgkmcnt(3)
	v_mfma_f32_32x32x16_f16 v[18:33], v[154:157], v[166:169], v[18:33]
	ds_read_b128 v[154:157], v147 offset:36960
	global_load_dwordx4 v[86:89], v142, s[8:9] offset:768
	v_mfma_f32_32x32x16_f16 v[2:17], v[162:165], v[166:169], v[2:17]
	ds_read_b128 v[162:165], v147 offset:41568
	ds_read_b128 v[166:169], v146 offset:4704
	s_waitcnt vmcnt(8)
	ds_write_b128 v144, v[118:121] offset:64512
	s_waitcnt lgkmcnt(3)
	v_mfma_f32_32x32x16_f16 v[50:65], v[154:157], v[158:161], v[50:65]
	global_load_dwordx4 v[90:93], v139, s[6:7] offset:768
	s_waitcnt lgkmcnt(2)
	v_mfma_f32_32x32x16_f16 v[34:49], v[162:165], v[158:161], v[34:49]
	s_waitcnt vmcnt(8)
	ds_write_b128 v144, v[122:125] offset:32256
	s_waitcnt lgkmcnt(2)
	v_mfma_f32_32x32x16_f16 v[18:33], v[154:157], v[166:169], v[18:33]
	global_load_dwordx4 v[94:97], v143, s[8:9] offset:768
	v_mfma_f32_32x32x16_f16 v[2:17], v[162:165], v[166:169], v[2:17]
	s_waitcnt vmcnt(8)
	ds_write_b128 v145, v[126:129] offset:64512
	s_setprio 0
	s_waitcnt lgkmcnt(0)
	s_barrier
; #define GEMM_GLOAD(P, kt_) { GEMM_GL1(P, 0, kt_) GEMM_GL1(P, 1, kt_) GEMM_GL1(P, 2, kt_) GEMM_GL1(P, 3, kt_) }
; #define GEMM_LSTORE(P, buf_) { GEMM_LS1(P, 0, buf_) GEMM_LS1(P, 1, buf_) GEMM_LS1(P, 2, buf_) GEMM_LS1(P, 3, buf_) }
; template <bool DEEP>
; DI void gemm_mainloop_t(const u16* __restrict__ Ag, int lda, const u16* __restrict__ Bg, int ldb, int K, char* ldsraw,
;                         f32x16 (&acc)[2][2], int akstep) {
;     ...
;   if (DEEP) {
;     uint4 ya0, ya1, ya2, ya3, yb0, yb1, yb2, yb3;
;     GEMM_GLOAD(x, 0);
;     GEMM_GLOAD(y, 1);
;     GEMM_LSTORE(x, 0);
;     __syncthreads();
;     for (int kt = 0; kt < nk; kt += 2) {
;       if (kt + 2 < nk) GEMM_GLOAD(x, kt + 2);
;       GEMM_COMPUTE(0);
;       GEMM_LSTORE(y, 1);
;       __syncthreads();
;       if (kt + 3 < nk) GEMM_GLOAD(y, kt + 3);
;       GEMM_COMPUTE(1);
;       if (kt + 2 < nk) GEMM_LSTORE(x, 0);
;       __syncthreads();
;     }
	s_setprio 1
	ds_read_b128 v[154:157], v147 offset:55296
	ds_read_b128 v[158:161], v146 offset:18432
	ds_read_b128 v[162:165], v147 offset:59904
	ds_read_b128 v[166:169], v146 offset:23040
	s_waitcnt lgkmcnt(2)
	v_mfma_f32_32x32x16_f16 v[50:65], v[154:157], v[158:161], v[50:65]
	global_load_dwordx4 v[98:101], v136, s[6:7] offset:896
	s_waitcnt lgkmcnt(1)
	v_mfma_f32_32x32x16_f16 v[34:49], v[162:165], v[158:161], v[34:49]
	ds_read_b128 v[158:161], v146 offset:18464
	s_waitcnt vmcnt(8)
	ds_write_b128 v144, v[66:69]
	s_waitcnt lgkmcnt(2)
	v_mfma_f32_32x32x16_f16 v[18:33], v[154:157], v[166:169], v[18:33]
	ds_read_b128 v[154:157], v147 offset:55328
	global_load_dwordx4 v[102:105], v140, s[8:9] offset:896
	v_mfma_f32_32x32x16_f16 v[2:17], v[162:165], v[166:169], v[2:17]
	ds_read_b128 v[162:165], v147 offset:59936
	ds_read_b128 v[166:169], v146 offset:23072
	s_waitcnt vmcnt(8)
	ds_write_b128 v144, v[70:73] offset:36864
	s_waitcnt lgkmcnt(3)
	v_mfma_f32_32x32x16_f16 v[50:65], v[154:157], v[158:161], v[50:65]
	global_load_dwordx4 v[106:109], v137, s[6:7] offset:896
	s_waitcnt lgkmcnt(2)
	v_mfma_f32_32x32x16_f16 v[34:49], v[162:165], v[158:161], v[34:49]
	ds_read_b128 v[158:161], v146 offset:18496
	s_waitcnt vmcnt(8)
	ds_write_b128 v144, v[74:77] offset:4608
	s_waitcnt lgkmcnt(3)
	v_mfma_f32_32x32x16_f16 v[18:33], v[154:157], v[166:169], v[18:33]
	ds_read_b128 v[154:157], v147 offset:55360
	global_load_dwordx4 v[110:113], v141, s[8:9] offset:896
	v_mfma_f32_32x32x16_f16 v[2:17], v[162:165], v[166:169], v[2:17]
	ds_read_b128 v[162:165], v147 offset:59968
	ds_read_b128 v[166:169], v146 offset:23104
	s_waitcnt vmcnt(8)
	ds_write_b128 v144, v[78:81] offset:41472
	s_waitcnt lgkmcnt(3)
	v_mfma_f32_32x32x16_f16 v[50:65], v[154:157], v[158:161], v[50:65]
	global_load_dwordx4 v[114:117], v138, s[6:7] offset:896
	s_waitcnt lgkmcnt(2)
	v_mfma_f32_32x32x16_f16 v[34:49], v[162:165], v[158:161], v[34:49]
	ds_read_b128 v[158:161], v146 offset:18528
	s_waitcnt vmcnt(8)
	ds_write_b128 v144, v[82:85] offset:9216
	s_waitcnt lgkmcnt(3)
	v_mfma_f32_32x32x16_f16 v[18:33], v[154:157], v[166:169], v[18:33]
	ds_read_b128 v[154:157], v147 offset:55392
	global_load_dwordx4 v[118:121], v142, s[8:9] offset:896
	v_mfma_f32_32x32x16_f16 v[2:17], v[162:165], v[166:169], v[2:17]
	ds_read_b128 v[162:165], v147 offset:60000
	ds_read_b128 v[166:169], v146 offset:23136
	s_waitcnt vmcnt(8)
	ds_write_b128 v144, v[86:89] offset:46080
	s_waitcnt lgkmcnt(3)
	v_mfma_f32_32x32x16_f16 v[50:65], v[154:157], v[158:161], v[50:65]
	global_load_dwordx4 v[122:125], v139, s[6:7] offset:896
	s_waitcnt lgkmcnt(2)
	v_mfma_f32_32x32x16_f16 v[34:49], v[162:165], v[158:161], v[34:49]
	s_waitcnt vmcnt(8)
	ds_write_b128 v144, v[90:93] offset:13824
	s_waitcnt lgkmcnt(2)
	v_mfma_f32_32x32x16_f16 v[18:33], v[154:157], v[166:169], v[18:33]
	global_load_dwordx4 v[126:129], v143, s[8:9] offset:896
	v_mfma_f32_32x32x16_f16 v[2:17], v[162:165], v[166:169], v[2:17]
	s_waitcnt vmcnt(8)
	ds_write_b128 v144, v[94:97] offset:50688
	s_setprio 0
	s_waitcnt lgkmcnt(0)
	s_barrier
	s_setprio 1
	ds_read_b128 v[154:157], v147 offset:36864
	ds_read_b128 v[158:161], v146
	ds_read_b128 v[162:165], v147 offset:41472
	ds_read_b128 v[166:169], v146 offset:4608
	s_waitcnt lgkmcnt(2)
	v_mfma_f32_32x32x16_f16 v[50:65], v[154:157], v[158:161], v[50:65]
	global_load_dwordx4 v[66:69], v136, s[6:7] offset:1024
	s_waitcnt lgkmcnt(1)
	v_mfma_f32_32x32x16_f16 v[34:49], v[162:165], v[158:161], v[34:49]
	ds_read_b128 v[158:161], v146 offset:32
	s_waitcnt vmcnt(8)
	ds_write_b128 v144, v[98:101] offset:18432
	s_waitcnt lgkmcnt(2)
	v_mfma_f32_32x32x16_f16 v[18:33], v[154:157], v[166:169], v[18:33]
	ds_read_b128 v[154:157], v147 offset:36896
	global_load_dwordx4 v[70:73], v140, s[8:9] offset:1024
	v_mfma_f32_32x32x16_f16 v[2:17], v[162:165], v[166:169], v[2:17]
	ds_read_b128 v[162:165], v147 offset:41504
	ds_read_b128 v[166:169], v146 offset:4640
	s_waitcnt vmcnt(8)
	ds_write_b128 v144, v[102:105] offset:55296
	s_waitcnt lgkmcnt(3)
	v_mfma_f32_32x32x16_f16 v[50:65], v[154:157], v[158:161], v[50:65]
	global_load_dwordx4 v[74:77], v137, s[6:7] offset:1024
	s_waitcnt lgkmcnt(2)
	v_mfma_f32_32x32x16_f16 v[34:49], v[162:165], v[158:161], v[34:49]
	ds_read_b128 v[158:161], v146 offset:64
	s_waitcnt vmcnt(8)
	ds_write_b128 v144, v[106:109] offset:23040
	s_waitcnt lgkmcnt(3)
	v_mfma_f32_32x32x16_f16 v[18:33], v[154:157], v[166:169], v[18:33]
	ds_read_b128 v[154:157], v147 offset:36928
	global_load_dwordx4 v[78:81], v141, s[8:9] offset:1024
	v_mfma_f32_32x32x16_f16 v[2:17], v[162:165], v[166:169], v[2:17]
	ds_read_b128 v[162:165], v147 offset:41536
	ds_read_b128 v[166:169], v146 offset:4672
	s_waitcnt vmcnt(8)
	ds_write_b128 v144, v[110:113] offset:59904
	s_waitcnt lgkmcnt(3)
	v_mfma_f32_32x32x16_f16 v[50:65], v[154:157], v[158:161], v[50:65]
	global_load_dwordx4 v[82:85], v138, s[6:7] offset:1024
	s_waitcnt lgkmcnt(2)
	v_mfma_f32_32x32x16_f16 v[34:49], v[162:165], v[158:161], v[34:49]
	ds_read_b128 v[158:161], v146 offset:96
	s_waitcnt vmcnt(8)
	ds_write_b128 v144, v[114:117] offset:27648
	s_waitcnt lgkmcnt(3)
	v_mfma_f32_32x32x16_f16 v[18:33], v[154:157], v[166:169], v[18:33]
	ds_read_b128 v[154:157], v147 offset:36960
	global_load_dwordx4 v[86:89], v142, s[8:9] offset:1024
	v_mfma_f32_32x32x16_f16 v[2:17], v[162:165], v[166:169], v[2:17]
	ds_read_b128 v[162:165], v147 offset:41568
	ds_read_b128 v[166:169], v146 offset:4704
	s_waitcnt vmcnt(8)
	ds_write_b128 v144, v[118:121] offset:64512
	s_waitcnt lgkmcnt(3)
	v_mfma_f32_32x32x16_f16 v[50:65], v[154:157], v[158:161], v[50:65]
	global_load_dwordx4 v[90:93], v139, s[6:7] offset:1024
	s_waitcnt lgkmcnt(2)
	v_mfma_f32_32x32x16_f16 v[34:49], v[162:165], v[158:161], v[34:49]
	s_waitcnt vmcnt(8)
	ds_write_b128 v144, v[122:125] offset:32256
	s_waitcnt lgkmcnt(2)
	v_mfma_f32_32x32x16_f16 v[18:33], v[154:157], v[166:169], v[18:33]
	global_load_dwordx4 v[94:97], v143, s[8:9] offset:1024
	v_mfma_f32_32x32x16_f16 v[2:17], v[162:165], v[166:169], v[2:17]
	s_waitcnt vmcnt(8)
	ds_write_b128 v145, v[126:129] offset:64512
	s_setprio 0
	s_waitcnt lgkmcnt(0)
	s_barrier
; #define GEMM_GLOAD(P, kt_) { GEMM_GL1(P, 0, kt_) GEMM_GL1(P, 1, kt_) GEMM_GL1(P, 2, kt_) GEMM_GL1(P, 3, kt_) }
; #define GEMM_LSTORE(P, buf_) { GEMM_LS1(P, 0, buf_) GEMM_LS1(P, 1, buf_) GEMM_LS1(P, 2, buf_) GEMM_LS1(P, 3, buf_) }
; template <bool DEEP>
; DI void gemm_mainloop_t(const u16* __restrict__ Ag, int lda, const u16* __restrict__ Bg, int ldb, int K, char* ldsraw,
;                         f32x16 (&acc)[2][2], int akstep) {
;     ...
;   if (DEEP) {
;     uint4 ya0, ya1, ya2, ya3, yb0, yb1, yb2, yb3;
;     GEMM_GLOAD(x, 0);
;     GEMM_GLOAD(y, 1);
;     GEMM_LSTORE(x, 0);
;     __syncthreads();
;     for (int kt = 0; kt < nk; kt += 2) {
;       if (kt + 2 < nk) GEMM_GLOAD(x, kt + 2);
;       GEMM_COMPUTE(0);
;       GEMM_LSTORE(y, 1);
;       __syncthreads();
;       if (kt + 3 < nk) GEMM_GLOAD(y, kt + 3);
;       GEMM_COMPUTE(1);
;       if (kt + 2 < nk) GEMM_LSTORE(x, 0);
;       __syncthreads();
;     }
	s_setprio 1
	ds_read_b128 v[154:157], v147 offset:55296
	ds_read_b128 v[158:161], v146 offset:18432
	ds_read_b128 v[162:165], v147 offset:59904
	ds_read_b128 v[166:169], v146 offset:23040
	s_waitcnt lgkmcnt(2)
	v_mfma_f32_32x32x16_f16 v[50:65], v[154:157], v[158:161], v[50:65]
	global_load_dwordx4 v[98:101], v136, s[6:7] offset:1152
	s_waitcnt lgkmcnt(1)
	v_mfma_f32_32x32x16_f16 v[34:49], v[162:165], v[158:161], v[34:49]
	ds_read_b128 v[158:161], v146 offset:18464
	s_waitcnt vmcnt(8)
	ds_write_b128 v144, v[66:69]
	s_waitcnt lgkmcnt(2)
	v_mfma_f32_32x32x16_f16 v[18:33], v[154:157], v[166:169], v[18:33]
	ds_read_b128 v[154:157], v147 offset:55328
	global_load_dwordx4 v[102:105], v140, s[8:9] offset:1152
	v_mfma_f32_32x32x16_f16 v[2:17], v[162:165], v[166:169], v[2:17]
	ds_read_b128 v[162:165], v147 offset:59936
	ds_read_b128 v[166:169], v146 offset:23072
	s_waitcnt vmcnt(8)
	ds_write_b128 v144, v[70:73] offset:36864
	s_waitcnt lgkmcnt(3)
	v_mfma_f32_32x32x16_f16 v[50:65], v[154:157], v[158:161], v[50:65]
	global_load_dwordx4 v[106:109], v137, s[6:7] offset:1152
	s_waitcnt lgkmcnt(2)
	v_mfma_f32_32x32x16_f16 v[34:49], v[162:165], v[158:161], v[34:49]
	ds_read_b128 v[158:161], v146 offset:18496
	s_waitcnt vmcnt(8)
	ds_write_b128 v144, v[74:77] offset:4608
	s_waitcnt lgkmcnt(3)
	v_mfma_f32_32x32x16_f16 v[18:33], v[154:157], v[166:169], v[18:33]
	ds_read_b128 v[154:157], v147 offset:55360
	global_load_dwordx4 v[110:113], v141, s[8:9] offset:1152
	v_mfma_f32_32x32x16_f16 v[2:17], v[162:165], v[166:169], v[2:17]
	ds_read_b128 v[162:165], v147 offset:59968
	ds_read_b128 v[166:169], v146 offset:23104
	s_waitcnt vmcnt(8)
	ds_write_b128 v144, v[78:81] offset:41472
	s_waitcnt lgkmcnt(3)
	v_mfma_f32_32x32x16_f16 v[50:65], v[154:157], v[158:161], v[50:65]
	global_load_dwordx4 v[114:117], v138, s[6:7] offset:1152
	s_waitcnt lgkmcnt(2)
	v_mfma_f32_32x32x16_f16 v[34:49], v[162:165], v[158:161], v[34:49]
	ds_read_b128 v[158:161], v146 offset:18528
	s_waitcnt vmcnt(8)
	ds_write_b128 v144, v[82:85] offset:9216
	s_waitcnt lgkmcnt(3)
	v_mfma_f32_32x32x16_f16 v[18:33], v[154:157], v[166:169], v[18:33]
	ds_read_b128 v[154:157], v147 offset:55392
	global_load_dwordx4 v[118:121], v142, s[8:9] offset:1152
	v_mfma_f32_32x32x16_f16 v[2:17], v[162:165], v[166:169], v[2:17]
	ds_read_b128 v[162:165], v147 offset:60000
	ds_read_b128 v[166:169], v146 offset:23136
	s_waitcnt vmcnt(8)
	ds_write_b128 v144, v[86:89] offset:46080
	s_waitcnt lgkmcnt(3)
	v_mfma_f32_32x32x16_f16 v[50:65], v[154:157], v[158:161], v[50:65]
	global_load_dwordx4 v[122:125], v139, s[6:7] offset:1152
	s_waitcnt lgkmcnt(2)
	v_mfma_f32_32x32x16_f16 v[34:49], v[162:165], v[158:161], v[34:49]
	s_waitcnt vmcnt(8)
	ds_write_b128 v144, v[90:93] offset:13824
	s_waitcnt lgkmcnt(2)
	v_mfma_f32_32x32x16_f16 v[18:33], v[154:157], v[166:169], v[18:33]
	global_load_dwordx4 v[126:129], v143, s[8:9] offset:1152
	v_mfma_f32_32x32x16_f16 v[2:17], v[162:165], v[166:169], v[2:17]
	s_waitcnt vmcnt(8)
	ds_write_b128 v144, v[94:97] offset:50688
	s_setprio 0
	s_waitcnt lgkmcnt(0)
	s_barrier
	s_setprio 1
	ds_read_b128 v[154:157], v147 offset:36864
	ds_read_b128 v[158:161], v146
	ds_read_b128 v[162:165], v147 offset:41472
	ds_read_b128 v[166:169], v146 offset:4608
	s_waitcnt lgkmcnt(2)
	v_mfma_f32_32x32x16_f16 v[50:65], v[154:157], v[158:161], v[50:65]
	global_load_dwordx4 v[66:69], v136, s[6:7] offset:1280
	s_waitcnt lgkmcnt(1)
	v_mfma_f32_32x32x16_f16 v[34:49], v[162:165], v[158:161], v[34:49]
	ds_read_b128 v[158:161], v146 offset:32
	s_waitcnt vmcnt(8)
	ds_write_b128 v144, v[98:101] offset:18432
	s_waitcnt lgkmcnt(2)
	v_mfma_f32_32x32x16_f16 v[18:33], v[154:157], v[166:169], v[18:33]
	ds_read_b128 v[154:157], v147 offset:36896
	global_load_dwordx4 v[70:73], v140, s[8:9] offset:1280
	v_mfma_f32_32x32x16_f16 v[2:17], v[162:165], v[166:169], v[2:17]
	ds_read_b128 v[162:165], v147 offset:41504
	ds_read_b128 v[166:169], v146 offset:4640
	s_waitcnt vmcnt(8)
	ds_write_b128 v144, v[102:105] offset:55296
	s_waitcnt lgkmcnt(3)
	v_mfma_f32_32x32x16_f16 v[50:65], v[154:157], v[158:161], v[50:65]
	global_load_dwordx4 v[74:77], v137, s[6:7] offset:1280
	s_waitcnt lgkmcnt(2)
	v_mfma_f32_32x32x16_f16 v[34:49], v[162:165], v[158:161], v[34:49]
	ds_read_b128 v[158:161], v146 offset:64
	s_waitcnt vmcnt(8)
	ds_write_b128 v144, v[106:109] offset:23040
	s_waitcnt lgkmcnt(3)
	v_mfma_f32_32x32x16_f16 v[18:33], v[154:157], v[166:169], v[18:33]
	ds_read_b128 v[154:157], v147 offset:36928
	global_load_dwordx4 v[78:81], v141, s[8:9] offset:1280
	v_mfma_f32_32x32x16_f16 v[2:17], v[162:165], v[166:169], v[2:17]
	ds_read_b128 v[162:165], v147 offset:41536
	ds_read_b128 v[166:169], v146 offset:4672
	s_waitcnt vmcnt(8)
	ds_write_b128 v144, v[110:113] offset:59904
	s_waitcnt lgkmcnt(3)
	v_mfma_f32_32x32x16_f16 v[50:65], v[154:157], v[158:161], v[50:65]
	global_load_dwordx4 v[82:85], v138, s[6:7] offset:1280
	s_waitcnt lgkmcnt(2)
	v_mfma_f32_32x32x16_f16 v[34:49], v[162:165], v[158:161], v[34:49]
	ds_read_b128 v[158:161], v146 offset:96
	s_waitcnt vmcnt(8)
	ds_write_b128 v144, v[114:117] offset:27648
	s_waitcnt lgkmcnt(3)
	v_mfma_f32_32x32x16_f16 v[18:33], v[154:157], v[166:169], v[18:33]
	ds_read_b128 v[154:157], v147 offset:36960
	global_load_dwordx4 v[86:89], v142, s[8:9] offset:1280
	v_mfma_f32_32x32x16_f16 v[2:17], v[162:165], v[166:169], v[2:17]
	ds_read_b128 v[162:165], v147 offset:41568
	ds_read_b128 v[166:169], v146 offset:4704
	s_waitcnt vmcnt(8)
	ds_write_b128 v144, v[118:121] offset:64512
	s_waitcnt lgkmcnt(3)
	v_mfma_f32_32x32x16_f16 v[50:65], v[154:157], v[158:161], v[50:65]
	global_load_dwordx4 v[90:93], v139, s[6:7] offset:1280
	s_waitcnt lgkmcnt(2)
	v_mfma_f32_32x32x16_f16 v[34:49], v[162:165], v[158:161], v[34:49]
	s_waitcnt vmcnt(8)
	ds_write_b128 v144, v[122:125] offset:32256
	s_waitcnt lgkmcnt(2)
	v_mfma_f32_32x32x16_f16 v[18:33], v[154:157], v[166:169], v[18:33]
	global_load_dwordx4 v[94:97], v143, s[8:9] offset:1280
	v_mfma_f32_32x32x16_f16 v[2:17], v[162:165], v[166:169], v[2:17]
	s_waitcnt vmcnt(8)
	ds_write_b128 v145, v[126:129] offset:64512
	s_setprio 0
	s_waitcnt lgkmcnt(0)
	s_barrier
; #define GEMM_GLOAD(P, kt_) { GEMM_GL1(P, 0, kt_) GEMM_GL1(P, 1, kt_) GEMM_GL1(P, 2, kt_) GEMM_GL1(P, 3, kt_) }
; #define GEMM_LSTORE(P, buf_) { GEMM_LS1(P, 0, buf_) GEMM_LS1(P, 1, buf_) GEMM_LS1(P, 2, buf_) GEMM_LS1(P, 3, buf_) }
; template <bool DEEP>
; DI void gemm_mainloop_t(const u16* __restrict__ Ag, int lda, const u16* __restrict__ Bg, int ldb, int K, char* ldsraw,
;                         f32x16 (&acc)[2][2], int akstep) {
;     ...
;   if (DEEP) {
;     uint4 ya0, ya1, ya2, ya3, yb0, yb1, yb2, yb3;
;     GEMM_GLOAD(x, 0);
;     GEMM_GLOAD(y, 1);
;     GEMM_LSTORE(x, 0);
;     __syncthreads();
;     for (int kt = 0; kt < nk; kt += 2) {
;       if (kt + 2 < nk) GEMM_GLOAD(x, kt + 2);
;       GEMM_COMPUTE(0);
;       GEMM_LSTORE(y, 1);
;       __syncthreads();
;       if (kt + 3 < nk) GEMM_GLOAD(y, kt + 3);
;       GEMM_COMPUTE(1);
;       if (kt + 2 < nk) GEMM_LSTORE(x, 0);
;       __syncthreads();
;     }
	s_setprio 1
	ds_read_b128 v[154:157], v147 offset:55296
	ds_read_b128 v[158:161], v146 offset:18432
	ds_read_b128 v[162:165], v147 offset:59904
	ds_read_b128 v[166:169], v146 offset:23040
	s_waitcnt lgkmcnt(2)
	v_mfma_f32_32x32x16_f16 v[50:65], v[154:157], v[158:161], v[50:65]
	global_load_dwordx4 v[98:101], v136, s[6:7] offset:1408
	s_waitcnt lgkmcnt(1)
	v_mfma_f32_32x32x16_f16 v[34:49], v[162:165], v[158:161], v[34:49]
	ds_read_b128 v[158:161], v146 offset:18464
	s_waitcnt vmcnt(8)
	ds_write_b128 v144, v[66:69]
	s_waitcnt lgkmcnt(2)
	v_mfma_f32_32x32x16_f16 v[18:33], v[154:157], v[166:169], v[18:33]
	ds_read_b128 v[154:157], v147 offset:55328
	global_load_dwordx4 v[102:105], v140, s[8:9] offset:1408
	v_mfma_f32_32x32x16_f16 v[2:17], v[162:165], v[166:169], v[2:17]
	ds_read_b128 v[162:165], v147 offset:59936
	ds_read_b128 v[166:169], v146 offset:23072
	s_waitcnt vmcnt(8)
	ds_write_b128 v144, v[70:73] offset:36864
	s_waitcnt lgkmcnt(3)
	v_mfma_f32_32x32x16_f16 v[50:65], v[154:157], v[158:161], v[50:65]
	global_load_dwordx4 v[106:109], v137, s[6:7] offset:1408
	s_waitcnt lgkmcnt(2)
	v_mfma_f32_32x32x16_f16 v[34:49], v[162:165], v[158:161], v[34:49]
	ds_read_b128 v[158:161], v146 offset:18496
	s_waitcnt vmcnt(8)
	ds_write_b128 v144, v[74:77] offset:4608
	s_waitcnt lgkmcnt(3)
	v_mfma_f32_32x32x16_f16 v[18:33], v[154:157], v[166:169], v[18:33]
	ds_read_b128 v[154:157], v147 offset:55360
	global_load_dwordx4 v[110:113], v141, s[8:9] offset:1408
	v_mfma_f32_32x32x16_f16 v[2:17], v[162:165], v[166:169], v[2:17]
	ds_read_b128 v[162:165], v147 offset:59968
	ds_read_b128 v[166:169], v146 offset:23104
	s_waitcnt vmcnt(8)
	ds_write_b128 v144, v[78:81] offset:41472
	s_waitcnt lgkmcnt(3)
	v_mfma_f32_32x32x16_f16 v[50:65], v[154:157], v[158:161], v[50:65]
	global_load_dwordx4 v[114:117], v138, s[6:7] offset:1408
	s_waitcnt lgkmcnt(2)
	v_mfma_f32_32x32x16_f16 v[34:49], v[162:165], v[158:161], v[34:49]
	ds_read_b128 v[158:161], v146 offset:18528
	s_waitcnt vmcnt(8)
	ds_write_b128 v144, v[82:85] offset:9216
	s_waitcnt lgkmcnt(3)
	v_mfma_f32_32x32x16_f16 v[18:33], v[154:157], v[166:169], v[18:33]
	ds_read_b128 v[154:157], v147 offset:55392
	global_load_dwordx4 v[118:121], v142, s[8:9] offset:1408
	v_mfma_f32_32x32x16_f16 v[2:17], v[162:165], v[166:169], v[2:17]
	ds_read_b128 v[162:165], v147 offset:60000
	ds_read_b128 v[166:169], v146 offset:23136
	s_waitcnt vmcnt(8)
	ds_write_b128 v144, v[86:89] offset:46080
	s_waitcnt lgkmcnt(3)
	v_mfma_f32_32x32x16_f16 v[50:65], v[154:157], v[158:161], v[50:65]
	global_load_dwordx4 v[122:125], v139, s[6:7] offset:1408
	s_waitcnt lgkmcnt(2)
	v_mfma_f32_32x32x16_f16 v[34:49], v[162:165], v[158:161], v[34:49]
	s_waitcnt vmcnt(8)
	ds_write_b128 v144, v[90:93] offset:13824
	s_waitcnt lgkmcnt(2)
	v_mfma_f32_32x32x16_f16 v[18:33], v[154:157], v[166:169], v[18:33]
	global_load_dwordx4 v[126:129], v143, s[8:9] offset:1408
	v_mfma_f32_32x32x16_f16 v[2:17], v[162:165], v[166:169], v[2:17]
	s_waitcnt vmcnt(8)
	ds_write_b128 v144, v[94:97] offset:50688
	s_setprio 0
	s_waitcnt lgkmcnt(0)
	s_barrier
	s_setprio 1
	ds_read_b128 v[154:157], v147 offset:36864
	ds_read_b128 v[158:161], v146
	ds_read_b128 v[162:165], v147 offset:41472
	ds_read_b128 v[166:169], v146 offset:4608
	s_waitcnt lgkmcnt(2)
	v_mfma_f32_32x32x16_f16 v[50:65], v[154:157], v[158:161], v[50:65]
	global_load_dwordx4 v[66:69], v136, s[6:7] offset:1536
	s_waitcnt lgkmcnt(1)
	v_mfma_f32_32x32x16_f16 v[34:49], v[162:165], v[158:161], v[34:49]
	ds_read_b128 v[158:161], v146 offset:32
	s_waitcnt vmcnt(8)
	ds_write_b128 v144, v[98:101] offset:18432
	s_waitcnt lgkmcnt(2)
	v_mfma_f32_32x32x16_f16 v[18:33], v[154:157], v[166:169], v[18:33]
	ds_read_b128 v[154:157], v147 offset:36896
	global_load_dwordx4 v[70:73], v140, s[8:9] offset:1536
	v_mfma_f32_32x32x16_f16 v[2:17], v[162:165], v[166:169], v[2:17]
	ds_read_b128 v[162:165], v147 offset:41504
	ds_read_b128 v[166:169], v146 offset:4640
	s_waitcnt vmcnt(8)
	ds_write_b128 v144, v[102:105] offset:55296
	s_waitcnt lgkmcnt(3)
	v_mfma_f32_32x32x16_f16 v[50:65], v[154:157], v[158:161], v[50:65]
	global_load_dwordx4 v[74:77], v137, s[6:7] offset:1536
	s_waitcnt lgkmcnt(2)
	v_mfma_f32_32x32x16_f16 v[34:49], v[162:165], v[158:161], v[34:49]
	ds_read_b128 v[158:161], v146 offset:64
	s_waitcnt vmcnt(8)
	ds_write_b128 v144, v[106:109] offset:23040
	s_waitcnt lgkmcnt(3)
	v_mfma_f32_32x32x16_f16 v[18:33], v[154:157], v[166:169], v[18:33]
	ds_read_b128 v[154:157], v147 offset:36928
	global_load_dwordx4 v[78:81], v141, s[8:9] offset:1536
	v_mfma_f32_32x32x16_f16 v[2:17], v[162:165], v[166:169], v[2:17]
	ds_read_b128 v[162:165], v147 offset:41536
	ds_read_b128 v[166:169], v146 offset:4672
	s_waitcnt vmcnt(8)
	ds_write_b128 v144, v[110:113] offset:59904
	s_waitcnt lgkmcnt(3)
	v_mfma_f32_32x32x16_f16 v[50:65], v[154:157], v[158:161], v[50:65]
	global_load_dwordx4 v[82:85], v138, s[6:7] offset:1536
	s_waitcnt lgkmcnt(2)
	v_mfma_f32_32x32x16_f16 v[34:49], v[162:165], v[158:161], v[34:49]
	ds_read_b128 v[158:161], v146 offset:96
	s_waitcnt vmcnt(8)
	ds_write_b128 v144, v[114:117] offset:27648
	s_waitcnt lgkmcnt(3)
	v_mfma_f32_32x32x16_f16 v[18:33], v[154:157], v[166:169], v[18:33]
	ds_read_b128 v[154:157], v147 offset:36960
	global_load_dwordx4 v[86:89], v142, s[8:9] offset:1536
	v_mfma_f32_32x32x16_f16 v[2:17], v[162:165], v[166:169], v[2:17]
	ds_read_b128 v[162:165], v147 offset:41568
	ds_read_b128 v[166:169], v146 offset:4704
	s_waitcnt vmcnt(8)
	ds_write_b128 v144, v[118:121] offset:64512
	s_waitcnt lgkmcnt(3)
	v_mfma_f32_32x32x16_f16 v[50:65], v[154:157], v[158:161], v[50:65]
	global_load_dwordx4 v[90:93], v139, s[6:7] offset:1536
	s_waitcnt lgkmcnt(2)
	v_mfma_f32_32x32x16_f16 v[34:49], v[162:165], v[158:161], v[34:49]
	s_waitcnt vmcnt(8)
	ds_write_b128 v144, v[122:125] offset:32256
	s_waitcnt lgkmcnt(2)
	v_mfma_f32_32x32x16_f16 v[18:33], v[154:157], v[166:169], v[18:33]
	global_load_dwordx4 v[94:97], v143, s[8:9] offset:1536
	v_mfma_f32_32x32x16_f16 v[2:17], v[162:165], v[166:169], v[2:17]
	s_waitcnt vmcnt(8)
	ds_write_b128 v145, v[126:129] offset:64512
	s_setprio 0
	s_waitcnt lgkmcnt(0)
	s_barrier
; #define GEMM_GLOAD(P, kt_) { GEMM_GL1(P, 0, kt_) GEMM_GL1(P, 1, kt_) GEMM_GL1(P, 2, kt_) GEMM_GL1(P, 3, kt_) }
; #define GEMM_LSTORE(P, buf_) { GEMM_LS1(P, 0, buf_) GEMM_LS1(P, 1, buf_) GEMM_LS1(P, 2, buf_) GEMM_LS1(P, 3, buf_) }
; template <bool DEEP>
; DI void gemm_mainloop_t(const u16* __restrict__ Ag, int lda, const u16* __restrict__ Bg, int ldb, int K, char* ldsraw,
;                         f32x16 (&acc)[2][2], int akstep) {
;     ...
;   if (DEEP) {
;     uint4 ya0, ya1, ya2, ya3, yb0, yb1, yb2, yb3;
;     GEMM_GLOAD(x, 0);
;     GEMM_GLOAD(y, 1);
;     GEMM_LSTORE(x, 0);
;     __syncthreads();
;     for (int kt = 0; kt < nk; kt += 2) {
;       if (kt + 2 < nk) GEMM_GLOAD(x, kt + 2);
;       GEMM_COMPUTE(0);
;       GEMM_LSTORE(y, 1);
;       __syncthreads();
;       if (kt + 3 < nk) GEMM_GLOAD(y, kt + 3);
;       GEMM_COMPUTE(1);
;       if (kt + 2 < nk) GEMM_LSTORE(x, 0);
;       __syncthreads();
;     }
	s_setprio 1
	ds_read_b128 v[154:157], v147 offset:55296
	ds_read_b128 v[158:161], v146 offset:18432
	ds_read_b128 v[162:165], v147 offset:59904
	ds_read_b128 v[166:169], v146 offset:23040
	s_waitcnt lgkmcnt(2)
	v_mfma_f32_32x32x16_f16 v[50:65], v[154:157], v[158:161], v[50:65]
	global_load_dwordx4 v[98:101], v136, s[6:7] offset:1664
	s_waitcnt lgkmcnt(1)
	v_mfma_f32_32x32x16_f16 v[34:49], v[162:165], v[158:161], v[34:49]
	ds_read_b128 v[158:161], v146 offset:18464
	s_waitcnt vmcnt(8)
	ds_write_b128 v144, v[66:69]
	s_waitcnt lgkmcnt(2)
	v_mfma_f32_32x32x16_f16 v[18:33], v[154:157], v[166:169], v[18:33]
	ds_read_b128 v[154:157], v147 offset:55328
	global_load_dwordx4 v[102:105], v140, s[8:9] offset:1664
	v_mfma_f32_32x32x16_f16 v[2:17], v[162:165], v[166:169], v[2:17]
	ds_read_b128 v[162:165], v147 offset:59936
	ds_read_b128 v[166:169], v146 offset:23072
	s_waitcnt vmcnt(8)
	ds_write_b128 v144, v[70:73] offset:36864
	s_waitcnt lgkmcnt(3)
	v_mfma_f32_32x32x16_f16 v[50:65], v[154:157], v[158:161], v[50:65]
	global_load_dwordx4 v[106:109], v137, s[6:7] offset:1664
	s_waitcnt lgkmcnt(2)
	v_mfma_f32_32x32x16_f16 v[34:49], v[162:165], v[158:161], v[34:49]
	ds_read_b128 v[158:161], v146 offset:18496
	s_waitcnt vmcnt(8)
	ds_write_b128 v144, v[74:77] offset:4608
	s_waitcnt lgkmcnt(3)
	v_mfma_f32_32x32x16_f16 v[18:33], v[154:157], v[166:169], v[18:33]
	ds_read_b128 v[154:157], v147 offset:55360
	global_load_dwordx4 v[110:113], v141, s[8:9] offset:1664
	v_mfma_f32_32x32x16_f16 v[2:17], v[162:165], v[166:169], v[2:17]
	ds_read_b128 v[162:165], v147 offset:59968
	ds_read_b128 v[166:169], v146 offset:23104
	s_waitcnt vmcnt(8)
	ds_write_b128 v144, v[78:81] offset:41472
	s_waitcnt lgkmcnt(3)
	v_mfma_f32_32x32x16_f16 v[50:65], v[154:157], v[158:161], v[50:65]
	global_load_dwordx4 v[114:117], v138, s[6:7] offset:1664
	s_waitcnt lgkmcnt(2)
	v_mfma_f32_32x32x16_f16 v[34:49], v[162:165], v[158:161], v[34:49]
	ds_read_b128 v[158:161], v146 offset:18528
	s_waitcnt vmcnt(8)
	ds_write_b128 v144, v[82:85] offset:9216
	s_waitcnt lgkmcnt(3)
	v_mfma_f32_32x32x16_f16 v[18:33], v[154:157], v[166:169], v[18:33]
	ds_read_b128 v[154:157], v147 offset:55392
	global_load_dwordx4 v[118:121], v142, s[8:9] offset:1664
	v_mfma_f32_32x32x16_f16 v[2:17], v[162:165], v[166:169], v[2:17]
	ds_read_b128 v[162:165], v147 offset:60000
	ds_read_b128 v[166:169], v146 offset:23136
	s_waitcnt vmcnt(8)
	ds_write_b128 v144, v[86:89] offset:46080
	s_waitcnt lgkmcnt(3)
	v_mfma_f32_32x32x16_f16 v[50:65], v[154:157], v[158:161], v[50:65]
	global_load_dwordx4 v[122:125], v139, s[6:7] offset:1664
	s_waitcnt lgkmcnt(2)
	v_mfma_f32_32x32x16_f16 v[34:49], v[162:165], v[158:161], v[34:49]
	s_waitcnt vmcnt(8)
	ds_write_b128 v144, v[90:93] offset:13824
	s_waitcnt lgkmcnt(2)
	v_mfma_f32_32x32x16_f16 v[18:33], v[154:157], v[166:169], v[18:33]
	global_load_dwordx4 v[126:129], v143, s[8:9] offset:1664
	v_mfma_f32_32x32x16_f16 v[2:17], v[162:165], v[166:169], v[2:17]
	s_waitcnt vmcnt(8)
	ds_write_b128 v144, v[94:97] offset:50688
	s_setprio 0
	s_waitcnt lgkmcnt(0)
	s_barrier
	s_setprio 1
	ds_read_b128 v[154:157], v147 offset:36864
	ds_read_b128 v[158:161], v146
	ds_read_b128 v[162:165], v147 offset:41472
	ds_read_b128 v[166:169], v146 offset:4608
	s_waitcnt lgkmcnt(2)
	v_mfma_f32_32x32x16_f16 v[50:65], v[154:157], v[158:161], v[50:65]
	global_load_dwordx4 v[66:69], v136, s[6:7] offset:1792
	s_waitcnt lgkmcnt(1)
	v_mfma_f32_32x32x16_f16 v[34:49], v[162:165], v[158:161], v[34:49]
	ds_read_b128 v[158:161], v146 offset:32
	s_waitcnt vmcnt(8)
	ds_write_b128 v144, v[98:101] offset:18432
	s_waitcnt lgkmcnt(2)
	v_mfma_f32_32x32x16_f16 v[18:33], v[154:157], v[166:169], v[18:33]
	ds_read_b128 v[154:157], v147 offset:36896
	global_load_dwordx4 v[70:73], v140, s[8:9] offset:1792
	v_mfma_f32_32x32x16_f16 v[2:17], v[162:165], v[166:169], v[2:17]
	ds_read_b128 v[162:165], v147 offset:41504
	ds_read_b128 v[166:169], v146 offset:4640
	s_waitcnt vmcnt(8)
	ds_write_b128 v144, v[102:105] offset:55296
	s_waitcnt lgkmcnt(3)
	v_mfma_f32_32x32x16_f16 v[50:65], v[154:157], v[158:161], v[50:65]
	global_load_dwordx4 v[74:77], v137, s[6:7] offset:1792
	s_waitcnt lgkmcnt(2)
	v_mfma_f32_32x32x16_f16 v[34:49], v[162:165], v[158:161], v[34:49]
	ds_read_b128 v[158:161], v146 offset:64
	s_waitcnt vmcnt(8)
	ds_write_b128 v144, v[106:109] offset:23040
	s_waitcnt lgkmcnt(3)
	v_mfma_f32_32x32x16_f16 v[18:33], v[154:157], v[166:169], v[18:33]
	ds_read_b128 v[154:157], v147 offset:36928
	global_load_dwordx4 v[78:81], v141, s[8:9] offset:1792
	v_mfma_f32_32x32x16_f16 v[2:17], v[162:165], v[166:169], v[2:17]
	ds_read_b128 v[162:165], v147 offset:41536
	ds_read_b128 v[166:169], v146 offset:4672
	s_waitcnt vmcnt(8)
	ds_write_b128 v144, v[110:113] offset:59904
	s_waitcnt lgkmcnt(3)
	v_mfma_f32_32x32x16_f16 v[50:65], v[154:157], v[158:161], v[50:65]
	global_load_dwordx4 v[82:85], v138, s[6:7] offset:1792
	s_waitcnt lgkmcnt(2)
	v_mfma_f32_32x32x16_f16 v[34:49], v[162:165], v[158:161], v[34:49]
	ds_read_b128 v[158:161], v146 offset:96
	s_waitcnt vmcnt(8)
	ds_write_b128 v144, v[114:117] offset:27648
	s_waitcnt lgkmcnt(3)
	v_mfma_f32_32x32x16_f16 v[18:33], v[154:157], v[166:169], v[18:33]
	ds_read_b128 v[154:157], v147 offset:36960
	global_load_dwordx4 v[86:89], v142, s[8:9] offset:1792
	v_mfma_f32_32x32x16_f16 v[2:17], v[162:165], v[166:169], v[2:17]
	ds_read_b128 v[162:165], v147 offset:41568
	ds_read_b128 v[166:169], v146 offset:4704
	s_waitcnt vmcnt(8)
	ds_write_b128 v144, v[118:121] offset:64512
	s_waitcnt lgkmcnt(3)
	v_mfma_f32_32x32x16_f16 v[50:65], v[154:157], v[158:161], v[50:65]
	global_load_dwordx4 v[90:93], v139, s[6:7] offset:1792
	s_waitcnt lgkmcnt(2)
	v_mfma_f32_32x32x16_f16 v[34:49], v[162:165], v[158:161], v[34:49]
	s_waitcnt vmcnt(8)
	ds_write_b128 v144, v[122:125] offset:32256
	s_waitcnt lgkmcnt(2)
	v_mfma_f32_32x32x16_f16 v[18:33], v[154:157], v[166:169], v[18:33]
	global_load_dwordx4 v[94:97], v143, s[8:9] offset:1792
	v_mfma_f32_32x32x16_f16 v[2:17], v[162:165], v[166:169], v[2:17]
	s_waitcnt vmcnt(8)
	ds_write_b128 v145, v[126:129] offset:64512
	s_setprio 0
	s_waitcnt lgkmcnt(0)
	s_barrier
; #define GEMM_GLOAD(P, kt_) { GEMM_GL1(P, 0, kt_) GEMM_GL1(P, 1, kt_) GEMM_GL1(P, 2, kt_) GEMM_GL1(P, 3, kt_) }
; #define GEMM_LSTORE(P, buf_) { GEMM_LS1(P, 0, buf_) GEMM_LS1(P, 1, buf_) GEMM_LS1(P, 2, buf_) GEMM_LS1(P, 3, buf_) }
; template <bool DEEP>
; DI void gemm_mainloop_t(const u16* __restrict__ Ag, int lda, const u16* __restrict__ Bg, int ldb, int K, char* ldsraw,
;                         f32x16 (&acc)[2][2], int akstep) {
;     ...
;   if (DEEP) {
;     uint4 ya0, ya1, ya2, ya3, yb0, yb1, yb2, yb3;
;     GEMM_GLOAD(x, 0);
;     GEMM_GLOAD(y, 1);
;     GEMM_LSTORE(x, 0);
;     __syncthreads();
;     for (int kt = 0; kt < nk; kt += 2) {
;       if (kt + 2 < nk) GEMM_GLOAD(x, kt + 2);
;       GEMM_COMPUTE(0);
;       GEMM_LSTORE(y, 1);
;       __syncthreads();
;       if (kt + 3 < nk) GEMM_GLOAD(y, kt + 3);
;       GEMM_COMPUTE(1);
;       if (kt + 2 < nk) GEMM_LSTORE(x, 0);
;       __syncthreads();
;     }
	s_setprio 1
	ds_read_b128 v[154:157], v147 offset:55296
	ds_read_b128 v[158:161], v146 offset:18432
	ds_read_b128 v[162:165], v147 offset:59904
	ds_read_b128 v[166:169], v146 offset:23040
	s_waitcnt lgkmcnt(2)
	v_mfma_f32_32x32x16_f16 v[50:65], v[154:157], v[158:161], v[50:65]
	global_load_dwordx4 v[98:101], v136, s[6:7] offset:1920
	s_waitcnt lgkmcnt(1)
	v_mfma_f32_32x32x16_f16 v[34:49], v[162:165], v[158:161], v[34:49]
	ds_read_b128 v[158:161], v146 offset:18464
	s_waitcnt vmcnt(8)
	ds_write_b128 v144, v[66:69]
	s_waitcnt lgkmcnt(2)
	v_mfma_f32_32x32x16_f16 v[18:33], v[154:157], v[166:169], v[18:33]
	ds_read_b128 v[154:157], v147 offset:55328
	global_load_dwordx4 v[102:105], v140, s[8:9] offset:1920
	v_mfma_f32_32x32x16_f16 v[2:17], v[162:165], v[166:169], v[2:17]
	ds_read_b128 v[162:165], v147 offset:59936
	ds_read_b128 v[166:169], v146 offset:23072
	s_waitcnt vmcnt(8)
	ds_write_b128 v144, v[70:73] offset:36864
	s_waitcnt lgkmcnt(3)
	v_mfma_f32_32x32x16_f16 v[50:65], v[154:157], v[158:161], v[50:65]
	global_load_dwordx4 v[106:109], v137, s[6:7] offset:1920
	s_waitcnt lgkmcnt(2)
	v_mfma_f32_32x32x16_f16 v[34:49], v[162:165], v[158:161], v[34:49]
	ds_read_b128 v[158:161], v146 offset:18496
	s_waitcnt vmcnt(8)
	ds_write_b128 v144, v[74:77] offset:4608
	s_waitcnt lgkmcnt(3)
	v_mfma_f32_32x32x16_f16 v[18:33], v[154:157], v[166:169], v[18:33]
	ds_read_b128 v[154:157], v147 offset:55360
	global_load_dwordx4 v[110:113], v141, s[8:9] offset:1920
	v_mfma_f32_32x32x16_f16 v[2:17], v[162:165], v[166:169], v[2:17]
	ds_read_b128 v[162:165], v147 offset:59968
	ds_read_b128 v[166:169], v146 offset:23104
	s_waitcnt vmcnt(8)
	ds_write_b128 v144, v[78:81] offset:41472
	s_waitcnt lgkmcnt(3)
	v_mfma_f32_32x32x16_f16 v[50:65], v[154:157], v[158:161], v[50:65]
	global_load_dwordx4 v[114:117], v138, s[6:7] offset:1920
	s_waitcnt lgkmcnt(2)
	v_mfma_f32_32x32x16_f16 v[34:49], v[162:165], v[158:161], v[34:49]
	ds_read_b128 v[158:161], v146 offset:18528
	s_waitcnt vmcnt(8)
	ds_write_b128 v144, v[82:85] offset:9216
	s_waitcnt lgkmcnt(3)
	v_mfma_f32_32x32x16_f16 v[18:33], v[154:157], v[166:169], v[18:33]
	ds_read_b128 v[154:157], v147 offset:55392
	global_load_dwordx4 v[118:121], v142, s[8:9] offset:1920
	v_mfma_f32_32x32x16_f16 v[2:17], v[162:165], v[166:169], v[2:17]
	ds_read_b128 v[162:165], v147 offset:60000
	ds_read_b128 v[166:169], v146 offset:23136
	s_waitcnt vmcnt(8)
	ds_write_b128 v144, v[86:89] offset:46080
	s_waitcnt lgkmcnt(3)
	v_mfma_f32_32x32x16_f16 v[50:65], v[154:157], v[158:161], v[50:65]
	global_load_dwordx4 v[122:125], v139, s[6:7] offset:1920
	s_waitcnt lgkmcnt(2)
	v_mfma_f32_32x32x16_f16 v[34:49], v[162:165], v[158:161], v[34:49]
	s_waitcnt vmcnt(8)
	ds_write_b128 v144, v[90:93] offset:13824
	s_waitcnt lgkmcnt(2)
	v_mfma_f32_32x32x16_f16 v[18:33], v[154:157], v[166:169], v[18:33]
	global_load_dwordx4 v[126:129], v143, s[8:9] offset:1920
	v_mfma_f32_32x32x16_f16 v[2:17], v[162:165], v[166:169], v[2:17]
	s_waitcnt vmcnt(8)
	ds_write_b128 v144, v[94:97] offset:50688
	s_setprio 0
	s_waitcnt lgkmcnt(0)
	s_barrier
	s_setprio 1
	ds_read_b128 v[154:157], v147 offset:36864
	ds_read_b128 v[158:161], v146
	ds_read_b128 v[162:165], v147 offset:41472
	ds_read_b128 v[166:169], v146 offset:4608
	s_waitcnt lgkmcnt(2)
	v_mfma_f32_32x32x16_f16 v[50:65], v[154:157], v[158:161], v[50:65]
	s_waitcnt lgkmcnt(1)
	v_mfma_f32_32x32x16_f16 v[34:49], v[162:165], v[158:161], v[34:49]
	ds_read_b128 v[158:161], v146 offset:32
	s_waitcnt vmcnt(7)
	ds_write_b128 v144, v[98:101] offset:18432
	s_waitcnt lgkmcnt(2)
	v_mfma_f32_32x32x16_f16 v[18:33], v[154:157], v[166:169], v[18:33]
	ds_read_b128 v[154:157], v147 offset:36896
	v_mfma_f32_32x32x16_f16 v[2:17], v[162:165], v[166:169], v[2:17]
	ds_read_b128 v[162:165], v147 offset:41504
	ds_read_b128 v[166:169], v146 offset:4640
	s_waitcnt vmcnt(6)
	ds_write_b128 v144, v[102:105] offset:55296
	s_waitcnt lgkmcnt(3)
	v_mfma_f32_32x32x16_f16 v[50:65], v[154:157], v[158:161], v[50:65]
	s_waitcnt lgkmcnt(2)
	v_mfma_f32_32x32x16_f16 v[34:49], v[162:165], v[158:161], v[34:49]
	ds_read_b128 v[158:161], v146 offset:64
	s_waitcnt vmcnt(5)
	ds_write_b128 v144, v[106:109] offset:23040
	s_waitcnt lgkmcnt(3)
	v_mfma_f32_32x32x16_f16 v[18:33], v[154:157], v[166:169], v[18:33]
	ds_read_b128 v[154:157], v147 offset:36928
	v_mfma_f32_32x32x16_f16 v[2:17], v[162:165], v[166:169], v[2:17]
	ds_read_b128 v[162:165], v147 offset:41536
	ds_read_b128 v[166:169], v146 offset:4672
	s_waitcnt vmcnt(4)
	ds_write_b128 v144, v[110:113] offset:59904
	s_waitcnt lgkmcnt(3)
	v_mfma_f32_32x32x16_f16 v[50:65], v[154:157], v[158:161], v[50:65]
	s_waitcnt lgkmcnt(2)
	v_mfma_f32_32x32x16_f16 v[34:49], v[162:165], v[158:161], v[34:49]
	ds_read_b128 v[158:161], v146 offset:96
	s_waitcnt vmcnt(3)
	ds_write_b128 v144, v[114:117] offset:27648
	s_waitcnt lgkmcnt(3)
	v_mfma_f32_32x32x16_f16 v[18:33], v[154:157], v[166:169], v[18:33]
	ds_read_b128 v[154:157], v147 offset:36960
	v_mfma_f32_32x32x16_f16 v[2:17], v[162:165], v[166:169], v[2:17]
	ds_read_b128 v[162:165], v147 offset:41568
	ds_read_b128 v[166:169], v146 offset:4704
	s_waitcnt vmcnt(2)
	ds_write_b128 v144, v[118:121] offset:64512
	s_waitcnt lgkmcnt(3)
	v_mfma_f32_32x32x16_f16 v[50:65], v[154:157], v[158:161], v[50:65]
	s_waitcnt lgkmcnt(2)
	v_mfma_f32_32x32x16_f16 v[34:49], v[162:165], v[158:161], v[34:49]
	s_waitcnt vmcnt(1)
	ds_write_b128 v144, v[122:125] offset:32256
	s_waitcnt lgkmcnt(2)
	v_mfma_f32_32x32x16_f16 v[18:33], v[154:157], v[166:169], v[18:33]
	v_mfma_f32_32x32x16_f16 v[2:17], v[162:165], v[166:169], v[2:17]
	s_waitcnt vmcnt(0)
	ds_write_b128 v145, v[126:129] offset:64512
	s_setprio 0
	s_waitcnt lgkmcnt(0)
	s_barrier
; DI void phase5(const Params& p, int l, const float* xin, float* xout, char* lds) {
;     ...
; #pragma unroll
;     for (int mi = 0; mi < 2; ++mi) {
;       const size_t row = (size_t)mt * 128 + wm * 64 + mi * 32 + r;
; #pragma unroll
;       for (int ni = 0; ni < 2; ++ni)
; #pragma unroll
;         for (int a = 0; a < 4; ++a) {
;           const int col = nt * 128 + wn * 64 + ni * 32 + 8 * a + 4 * h;
;           float4 xv = *(const float4*)(xin + row * 1024 + col);
;           xv.x += acc[mi][ni][4 * a];
;           xv.y += acc[mi][ni][4 * a + 1];
;           xv.z += acc[mi][ni][4 * a + 2];
;           xv.w += acc[mi][ni][4 * a + 3];
;           *(float4*)(xout + row * 1024 + col) = xv;
;         }
	s_setprio 1
	ds_read_b128 v[154:157], v147 offset:55296
	ds_read_b128 v[158:161], v146 offset:18432
	ds_read_b128 v[162:165], v147 offset:59904
	ds_read_b128 v[166:169], v146 offset:23040
	s_waitcnt lgkmcnt(2)
	v_mfma_f32_32x32x16_f16 v[50:65], v[154:157], v[158:161], v[50:65]
	s_waitcnt lgkmcnt(1)
	v_mfma_f32_32x32x16_f16 v[34:49], v[162:165], v[158:161], v[34:49]
	ds_read_b128 v[158:161], v146 offset:18464
	s_waitcnt lgkmcnt(1)
	v_mfma_f32_32x32x16_f16 v[18:33], v[154:157], v[166:169], v[18:33]
	ds_read_b128 v[154:157], v147 offset:55328
	v_mfma_f32_32x32x16_f16 v[2:17], v[162:165], v[166:169], v[2:17]
	ds_read_b128 v[162:165], v147 offset:59936
	ds_read_b128 v[166:169], v146 offset:23072
	s_waitcnt lgkmcnt(2)
	v_mfma_f32_32x32x16_f16 v[50:65], v[154:157], v[158:161], v[50:65]
	s_waitcnt lgkmcnt(1)
	v_mfma_f32_32x32x16_f16 v[34:49], v[162:165], v[158:161], v[34:49]
	ds_read_b128 v[158:161], v146 offset:18496
	s_waitcnt lgkmcnt(1)
	v_mfma_f32_32x32x16_f16 v[18:33], v[154:157], v[166:169], v[18:33]
	ds_read_b128 v[154:157], v147 offset:55360
	v_mfma_f32_32x32x16_f16 v[2:17], v[162:165], v[166:169], v[2:17]
	ds_read_b128 v[162:165], v147 offset:59968
	ds_read_b128 v[166:169], v146 offset:23104
	s_waitcnt lgkmcnt(2)
	v_mfma_f32_32x32x16_f16 v[50:65], v[154:157], v[158:161], v[50:65]
	s_waitcnt lgkmcnt(1)
	v_mfma_f32_32x32x16_f16 v[34:49], v[162:165], v[158:161], v[34:49]
	ds_read_b128 v[158:161], v146 offset:18528
	s_waitcnt lgkmcnt(1)
	v_mfma_f32_32x32x16_f16 v[18:33], v[154:157], v[166:169], v[18:33]
	ds_read_b128 v[154:157], v147 offset:55392
	v_mfma_f32_32x32x16_f16 v[2:17], v[162:165], v[166:169], v[2:17]
	ds_read_b128 v[162:165], v147 offset:60000
	ds_read_b128 v[166:169], v146 offset:23136
	s_waitcnt lgkmcnt(2)
	v_mfma_f32_32x32x16_f16 v[50:65], v[154:157], v[158:161], v[50:65]
	s_waitcnt lgkmcnt(1)
	v_mfma_f32_32x32x16_f16 v[34:49], v[162:165], v[158:161], v[34:49]
	s_waitcnt lgkmcnt(0)
	v_mfma_f32_32x32x16_f16 v[18:33], v[154:157], v[166:169], v[18:33]
	v_mfma_f32_32x32x16_f16 v[2:17], v[162:165], v[166:169], v[2:17]
	s_setprio 0
	s_nop 1
	s_barrier
	v_and_b32_e32 v66, 63, v209
	v_lshrrev_b32_e32 v67, 4, v66
	v_and_b32_e32 v68, 15, v66
	v_lshrrev_b32_e32 v69, 7, v209
	v_lshl_add_u32 v69, v69, 6, v67
	s_lshl_b32 s6, s0, 7
	v_add_u32_e32 v69, s6, v69
	v_lshlrev_b32_e32 v70, 12, v69
	s_lshl_b32 s6, s5, 9
	v_and_b32_e32 v71, 64, v209
	v_lshl_add_u32 v70, v71, 2, v70
	v_lshl_add_u32 v70, v68, 4, v70
	v_add_u32_e32 v72, s6, v70
	v_mov_b32_e32 v73, v72
	v_lshrrev_b32_e32 v74, 6, v209
	v_mul_u32_u24_e32 v76, 0x2400, v74
	v_lshrrev_b32_e32 v74, 1, v74
	v_mul_u32_u24_e32 v74, 0x4800, v74
	v_add_u32_e32 v76, v76, v74
	v_add_u32_e32 v76, 0x4800, v76
	v_and_b32_e32 v75, 31, v66
	v_lshrrev_b32_e32 v74, 5, v66
	v_mul_u32_u24_e32 v75, 0x110, v75
	v_lshl_add_u32 v75, v74, 4, v75
	v_add_u32_e32 v75, v75, v76
	v_mul_u32_u24_e32 v77, 0x110, v67
	v_lshl_add_u32 v77, v68, 4, v77
	v_add_u32_e32 v77, v77, v76
	global_load_dwordx4 v[84:87], v72, s[12:13]
	v_add_u32_e32 v72, 0x4000, v72
	global_load_dwordx4 v[88:91], v72, s[12:13]
	v_add_u32_e32 v72, 0x4000, v72
	global_load_dwordx4 v[92:95], v72, s[12:13]
	v_add_u32_e32 v72, 0x4000, v72
	global_load_dwordx4 v[96:99], v72, s[12:13]
	v_add_u32_e32 v72, 0x4000, v72
	global_load_dwordx4 v[100:103], v72, s[12:13]
	v_add_u32_e32 v72, 0x4000, v72
	global_load_dwordx4 v[104:107], v72, s[12:13]
	v_add_u32_e32 v72, 0x4000, v72
	global_load_dwordx4 v[108:111], v72, s[12:13]
	v_add_u32_e32 v72, 0x4000, v72
	global_load_dwordx4 v[112:115], v72, s[12:13]
	v_add_u32_e32 v72, 0x4000, v72
	ds_write_b128 v75, v[50:53]
	ds_write_b128 v75, v[54:57] offset:32
	ds_write_b128 v75, v[58:61] offset:64
	ds_write_b128 v75, v[62:65] offset:96
	ds_write_b128 v75, v[34:37] offset:128
	ds_write_b128 v75, v[38:41] offset:160
	ds_write_b128 v75, v[42:45] offset:192
	ds_write_b128 v75, v[46:49] offset:224
	s_waitcnt lgkmcnt(0)
	ds_read_b128 v[34:37], v77
	ds_read_b128 v[38:41], v77 offset:1088
	ds_read_b128 v[42:45], v77 offset:2176
	ds_read_b128 v[46:49], v77 offset:3264
	ds_read_b128 v[50:53], v77 offset:4352
	ds_read_b128 v[54:57], v77 offset:5440
	ds_read_b128 v[58:61], v77 offset:6528
	ds_read_b128 v[62:65], v77 offset:7616
	s_waitcnt vmcnt(7) lgkmcnt(7)
	v_pk_add_f32 v[34:35], v[34:35], v[84:85]
	v_pk_add_f32 v[36:37], v[36:37], v[86:87]
	global_store_dwordx4 v73, v[34:37], s[10:11]
	v_add_u32_e32 v73, 0x4000, v73
	s_waitcnt vmcnt(7) lgkmcnt(6)
	v_pk_add_f32 v[38:39], v[38:39], v[88:89]
	v_pk_add_f32 v[40:41], v[40:41], v[90:91]
	global_store_dwordx4 v73, v[38:41], s[10:11]
	v_add_u32_e32 v73, 0x4000, v73
	s_waitcnt vmcnt(7) lgkmcnt(5)
; DI void phase5(const Params& p, int l, const float* xin, float* xout, char* lds) {
;     ...
; #pragma unroll
;     for (int mi = 0; mi < 2; ++mi) {
;       const size_t row = (size_t)mt * 128 + wm * 64 + mi * 32 + r;
; #pragma unroll
;       for (int ni = 0; ni < 2; ++ni)
; #pragma unroll
;         for (int a = 0; a < 4; ++a) {
;           const int col = nt * 128 + wn * 64 + ni * 32 + 8 * a + 4 * h;
;           float4 xv = *(const float4*)(xin + row * 1024 + col);
;           xv.x += acc[mi][ni][4 * a];
;           xv.y += acc[mi][ni][4 * a + 1];
;           xv.z += acc[mi][ni][4 * a + 2];
;           xv.w += acc[mi][ni][4 * a + 3];
;           *(float4*)(xout + row * 1024 + col) = xv;
;         }
;     }
;   }
; }
	v_pk_add_f32 v[42:43], v[42:43], v[92:93]
	v_pk_add_f32 v[44:45], v[44:45], v[94:95]
	global_store_dwordx4 v73, v[42:45], s[10:11]
	v_add_u32_e32 v73, 0x4000, v73
	s_waitcnt vmcnt(7) lgkmcnt(4)
	v_pk_add_f32 v[46:47], v[46:47], v[96:97]
	v_pk_add_f32 v[48:49], v[48:49], v[98:99]
	global_store_dwordx4 v73, v[46:49], s[10:11]
	v_add_u32_e32 v73, 0x4000, v73
	s_waitcnt vmcnt(7) lgkmcnt(3)
	v_pk_add_f32 v[50:51], v[50:51], v[100:101]
	v_pk_add_f32 v[52:53], v[52:53], v[102:103]
	global_store_dwordx4 v73, v[50:53], s[10:11]
	v_add_u32_e32 v73, 0x4000, v73
	s_waitcnt vmcnt(7) lgkmcnt(2)
	v_pk_add_f32 v[54:55], v[54:55], v[104:105]
	v_pk_add_f32 v[56:57], v[56:57], v[106:107]
	global_store_dwordx4 v73, v[54:57], s[10:11]
	v_add_u32_e32 v73, 0x4000, v73
	s_waitcnt vmcnt(7) lgkmcnt(1)
	v_pk_add_f32 v[58:59], v[58:59], v[108:109]
	v_pk_add_f32 v[60:61], v[60:61], v[110:111]
	global_store_dwordx4 v73, v[58:61], s[10:11]
	v_add_u32_e32 v73, 0x4000, v73
	s_waitcnt vmcnt(7) lgkmcnt(0)
	v_pk_add_f32 v[62:63], v[62:63], v[112:113]
	v_pk_add_f32 v[64:65], v[64:65], v[114:115]
	global_store_dwordx4 v73, v[62:65], s[10:11]
	v_add_u32_e32 v73, 0x4000, v73
	global_load_dwordx4 v[84:87], v72, s[12:13]
	v_add_u32_e32 v72, 0x4000, v72
	global_load_dwordx4 v[88:91], v72, s[12:13]
	v_add_u32_e32 v72, 0x4000, v72
	global_load_dwordx4 v[92:95], v72, s[12:13]
	v_add_u32_e32 v72, 0x4000, v72
	global_load_dwordx4 v[96:99], v72, s[12:13]
	v_add_u32_e32 v72, 0x4000, v72
	global_load_dwordx4 v[100:103], v72, s[12:13]
	v_add_u32_e32 v72, 0x4000, v72
	global_load_dwordx4 v[104:107], v72, s[12:13]
	v_add_u32_e32 v72, 0x4000, v72
	global_load_dwordx4 v[108:111], v72, s[12:13]
	v_add_u32_e32 v72, 0x4000, v72
	global_load_dwordx4 v[112:115], v72, s[12:13]
	v_add_u32_e32 v72, 0x4000, v72
	ds_write_b128 v75, v[18:21]
	ds_write_b128 v75, v[22:25] offset:32
	ds_write_b128 v75, v[26:29] offset:64
	ds_write_b128 v75, v[30:33] offset:96
	ds_write_b128 v75, v[2:5] offset:128
	ds_write_b128 v75, v[6:9] offset:160
	ds_write_b128 v75, v[10:13] offset:192
	ds_write_b128 v75, v[14:17] offset:224
	s_waitcnt lgkmcnt(0)
	ds_read_b128 v[2:5], v77
	ds_read_b128 v[6:9], v77 offset:1088
	ds_read_b128 v[10:13], v77 offset:2176
	ds_read_b128 v[14:17], v77 offset:3264
	ds_read_b128 v[18:21], v77 offset:4352
	ds_read_b128 v[22:25], v77 offset:5440
	ds_read_b128 v[26:29], v77 offset:6528
	ds_read_b128 v[30:33], v77 offset:7616
	s_waitcnt vmcnt(7) lgkmcnt(7)
	v_pk_add_f32 v[2:3], v[2:3], v[84:85]
	v_pk_add_f32 v[4:5], v[4:5], v[86:87]
	global_store_dwordx4 v73, v[2:5], s[10:11]
	v_add_u32_e32 v73, 0x4000, v73
	s_waitcnt vmcnt(7) lgkmcnt(6)
	v_pk_add_f32 v[6:7], v[6:7], v[88:89]
	v_pk_add_f32 v[8:9], v[8:9], v[90:91]
	global_store_dwordx4 v73, v[6:9], s[10:11]
	v_add_u32_e32 v73, 0x4000, v73
	s_waitcnt vmcnt(7) lgkmcnt(5)
	v_pk_add_f32 v[10:11], v[10:11], v[92:93]
	v_pk_add_f32 v[12:13], v[12:13], v[94:95]
	global_store_dwordx4 v73, v[10:13], s[10:11]
	v_add_u32_e32 v73, 0x4000, v73
	s_waitcnt vmcnt(7) lgkmcnt(4)
	v_pk_add_f32 v[14:15], v[14:15], v[96:97]
	v_pk_add_f32 v[16:17], v[16:17], v[98:99]
	global_store_dwordx4 v73, v[14:17], s[10:11]
	v_add_u32_e32 v73, 0x4000, v73
	s_waitcnt vmcnt(7) lgkmcnt(3)
	v_pk_add_f32 v[18:19], v[18:19], v[100:101]
	v_pk_add_f32 v[20:21], v[20:21], v[102:103]
	global_store_dwordx4 v73, v[18:21], s[10:11]
	v_add_u32_e32 v73, 0x4000, v73
	s_waitcnt vmcnt(7) lgkmcnt(2)
	v_pk_add_f32 v[22:23], v[22:23], v[104:105]
	v_pk_add_f32 v[24:25], v[24:25], v[106:107]
	global_store_dwordx4 v73, v[22:25], s[10:11]
	v_add_u32_e32 v73, 0x4000, v73
	s_waitcnt vmcnt(7) lgkmcnt(1)
	v_pk_add_f32 v[26:27], v[26:27], v[108:109]
	v_pk_add_f32 v[28:29], v[28:29], v[110:111]
	global_store_dwordx4 v73, v[26:29], s[10:11]
	v_add_u32_e32 v73, 0x4000, v73
	s_waitcnt vmcnt(7) lgkmcnt(0)
	v_pk_add_f32 v[30:31], v[30:31], v[112:113]
	v_pk_add_f32 v[32:33], v[32:33], v[114:115]
	global_store_dwordx4 v73, v[30:33], s[10:11]
	v_add_u32_e32 v73, 0x4000, v73
	s_add_i32 s4, s4, s30
	s_cmpk_lt_i32 s4, 0x400
	s_cbranch_scc1 .LBB0_1116
	v_readlane_b32 s0, v253, 1
	v_readlane_b32 s1, v253, 2
	v_lshlrev_b32_e32 v66, 4, v209
	s_nop 4
	global_load_dwordx4 v[166:169], v66, s[0:1]
	v_add_u32_e32 v66, 0x1000, v66
	global_load_dwordx4 v[170:173], v66, s[0:1]
	v_add_u32_e32 v66, 0x1000, v66
	global_load_dwordx4 v[174:177], v66, s[0:1]
	v_add_u32_e32 v66, 0x1000, v66
	global_load_dwordx4 v[178:181], v66, s[0:1]
	v_add_u32_e32 v66, 0x1000, v66
	global_load_dwordx4 v[182:185], v66, s[0:1]
	v_add_u32_e32 v66, 0x1000, v66
	s_waitcnt vmcnt(0)
	s_mov_b32 s19, s25
